# v23 with the store-data wait states restored in the EpiRes epilogues (s_nop where the serialized loads used to sit)
# baseline (speedup 1.0000x reference)
.LBB0_643:
	v_lshl_or_b32 v148, s58, 8, v151
	v_lshl_or_b32 v144, s60, 8, v152
	v_ashrrev_i32_e32 v149, 31, v148
	v_lshlrev_b64 v[168:169], 13, v[148:149]
	v_ashrrev_i32_e32 v145, 31, v144
	v_lshl_add_u64 v[160:161], s[52:53], 0, v[168:169]
	v_lshlrev_b64 v[146:147], 2, v[144:145]
	v_lshl_add_u64 v[170:171], v[160:161], 0, v[146:147]
	s_mov_b32 s98, 0x20000
	s_mov_b32 s99, 0
	s_mov_b32 s100, 0xa0000
	s_mov_b32 s101, 0
	global_load_dwordx4 v[184:187], v[170:171], off
	global_load_dwordx4 v[188:191], v[170:171], off offset:16
	global_load_dwordx4 v[192:195], v[170:171], off offset:512
	global_load_dwordx4 v[196:199], v[170:171], off offset:528
	v_lshl_add_u64 v[216:217], v[170:171], 0, s[98:99]
	global_load_dwordx4 v[200:203], v[216:217], off
	global_load_dwordx4 v[204:207], v[216:217], off offset:16
	global_load_dwordx4 v[208:211], v[216:217], off offset:512
	global_load_dwordx4 v[212:215], v[216:217], off offset:528
	s_nop 1
	v_lshlrev_b64 v[172:173], 12, v[148:149]
	v_lshl_add_u64 v[168:169], s[0:1], 0, v[168:169]
	v_lshl_add_u64 v[172:173], s[14:15], 0, v[172:173]
	v_lshl_add_u64 v[168:169], v[168:169], 0, v[146:147]
	v_lshl_add_u64 v[172:173], v[144:145], 1, v[172:173]
	s_waitcnt vmcnt(3)
	v_pk_add_f32 v[126:127], v[126:127], v[186:187]
	v_pk_add_f32 v[124:125], v[124:125], v[184:185]
	v_pk_add_f32 v[122:123], v[122:123], v[190:191]
	v_pk_add_f32 v[120:121], v[120:121], v[188:189]
	global_store_dwordx4 v[168:169], v[124:127], off
	global_store_dwordx4 v[168:169], v[120:123], off offset:16
	v_cvt_pk_bf16_f32 v160, v124, v125
	v_cvt_pk_bf16_f32 v161, v126, v127
	v_cvt_pk_bf16_f32 v162, v120, v121
	v_cvt_pk_bf16_f32 v163, v122, v123
	global_store_dwordx4 v[172:173], v[160:163], off
	s_nop 1
	s_nop 0
	v_mul_f32_e32 v125, v125, v125
	v_mul_f32_e32 v127, v127, v127
	v_mul_f32_e32 v121, v121, v121
	v_fmac_f32_e32 v125, v124, v124
	v_fmac_f32_e32 v127, v126, v126
	v_mul_f32_e32 v123, v123, v123
	v_fmac_f32_e32 v121, v120, v120
	v_add_f32_e32 v120, v125, v127
	v_fmac_f32_e32 v123, v122, v122
	v_add_f32_e32 v120, v120, v121
	v_add_f32_e32 v124, v123, v120
	v_pk_add_f32 v[118:119], v[118:119], v[194:195]
	v_pk_add_f32 v[116:117], v[116:117], v[192:193]
	v_pk_add_f32 v[120:121], v[112:113], v[196:197]
	v_mul_f32_e32 v112, v117, v117
	v_mul_f32_e32 v113, v119, v119
	v_pk_add_f32 v[122:123], v[114:115], v[198:199]
	v_lshl_add_u64 v[216:217], v[216:217], 0, s[98:99]
	global_load_dwordx4 v[184:187], v[216:217], off
	global_load_dwordx4 v[188:191], v[216:217], off offset:16
	global_load_dwordx4 v[192:195], v[216:217], off offset:512
	global_load_dwordx4 v[196:199], v[216:217], off offset:528
	v_mul_f32_e32 v114, v121, v121
	v_fmac_f32_e32 v112, v116, v116
	v_fmac_f32_e32 v113, v118, v118
	v_mul_f32_e32 v115, v123, v123
	v_fmac_f32_e32 v114, v120, v120
	v_add_f32_e32 v112, v112, v113
	v_add_f32_e32 v112, v112, v114
	v_fmac_f32_e32 v115, v122, v122
	v_add_f32_e32 v112, v115, v112
	v_add_f32_e32 v112, v124, v112
	ds_bpermute_b32 v113, v176, v112
	global_store_dwordx4 v[168:169], v[116:119], off offset:512
	global_store_dwordx4 v[168:169], v[120:123], off offset:528
	v_cvt_pk_bf16_f32 v114, v116, v117
	v_cvt_pk_bf16_f32 v115, v118, v119
	s_waitcnt lgkmcnt(0)
	v_add_f32_e32 v112, v112, v113
	ds_bpermute_b32 v113, v177, v112
	v_cvt_pk_bf16_f32 v116, v120, v121
	v_cvt_pk_bf16_f32 v117, v122, v123
	global_store_dwordx4 v[172:173], v[114:117], off offset:256
	s_and_saveexec_b64 s[58:59], s[6:7]
	s_cbranch_execz .LBB0_645
	v_lshl_add_u64 v[114:115], v[148:149], 2, s[16:17]
	s_waitcnt lgkmcnt(0)
	v_add_f32_e32 v112, v112, v113
	global_atomic_add_f32 v[114:115], v112, off
.LBB0_645:
	s_or_b64 exec, exec, s[58:59]
	v_or_b32_e32 v112, 16, v148
	s_waitcnt lgkmcnt(0)
	v_ashrrev_i32_e32 v113, 31, v112
	v_lshlrev_b64 v[122:123], 13, v[112:113]
	v_lshl_add_u64 v[114:115], s[52:53], 0, v[122:123]
	v_lshl_add_u64 v[124:125], v[114:115], 0, v[146:147]
	s_nop 1
	v_lshlrev_b64 v[126:127], 12, v[112:113]
	v_lshl_add_u64 v[122:123], s[0:1], 0, v[122:123]
	v_lshl_add_u64 v[126:127], s[14:15], 0, v[126:127]
	v_lshl_add_u64 v[122:123], v[122:123], 0, v[146:147]
	v_lshl_add_u64 v[126:127], v[144:145], 1, v[126:127]
	s_waitcnt vmcnt(10)
	v_pk_add_f32 v[110:111], v[110:111], v[202:203]
	v_pk_add_f32 v[108:109], v[108:109], v[200:201]
	v_pk_add_f32 v[106:107], v[106:107], v[206:207]
	v_pk_add_f32 v[104:105], v[104:105], v[204:205]
	global_store_dwordx4 v[122:123], v[108:111], off
	global_store_dwordx4 v[122:123], v[104:107], off offset:16
	v_cvt_pk_bf16_f32 v114, v108, v109
	v_cvt_pk_bf16_f32 v115, v110, v111
	v_cvt_pk_bf16_f32 v116, v104, v105
	v_cvt_pk_bf16_f32 v117, v106, v107
	global_store_dwordx4 v[126:127], v[114:117], off
	s_nop 1
	s_nop 0
	v_mul_f32_e32 v109, v109, v109
	v_mul_f32_e32 v111, v111, v111
	v_mul_f32_e32 v105, v105, v105
	v_fmac_f32_e32 v109, v108, v108
	v_fmac_f32_e32 v111, v110, v110
	v_mul_f32_e32 v107, v107, v107
	v_fmac_f32_e32 v105, v104, v104
	v_add_f32_e32 v104, v109, v111
	v_fmac_f32_e32 v107, v106, v106
	v_add_f32_e32 v104, v104, v105
	v_add_f32_e32 v108, v107, v104
	v_pk_add_f32 v[102:103], v[102:103], v[210:211]
	v_pk_add_f32 v[100:101], v[100:101], v[208:209]
	v_pk_add_f32 v[104:105], v[96:97], v[212:213]
	v_mul_f32_e32 v96, v101, v101
	v_mul_f32_e32 v97, v103, v103
	v_pk_add_f32 v[106:107], v[98:99], v[214:215]
	v_lshl_add_u64 v[216:217], v[216:217], 0, s[98:99]
	global_load_dwordx4 v[200:203], v[216:217], off
	global_load_dwordx4 v[204:207], v[216:217], off offset:16
	global_load_dwordx4 v[208:211], v[216:217], off offset:512
	global_load_dwordx4 v[212:215], v[216:217], off offset:528
	v_mul_f32_e32 v98, v105, v105
	v_fmac_f32_e32 v96, v100, v100
	v_fmac_f32_e32 v97, v102, v102
	v_mul_f32_e32 v99, v107, v107
	v_fmac_f32_e32 v98, v104, v104
	v_add_f32_e32 v96, v96, v97
	v_add_f32_e32 v96, v96, v98
	v_fmac_f32_e32 v99, v106, v106
	v_add_f32_e32 v96, v99, v96
	v_add_f32_e32 v96, v108, v96
	ds_bpermute_b32 v97, v176, v96
	global_store_dwordx4 v[122:123], v[100:103], off offset:512
	global_store_dwordx4 v[122:123], v[104:107], off offset:528
	v_cvt_pk_bf16_f32 v98, v100, v101
	v_cvt_pk_bf16_f32 v99, v102, v103
	s_waitcnt lgkmcnt(0)
	v_add_f32_e32 v96, v96, v97
	ds_bpermute_b32 v97, v177, v96
	v_cvt_pk_bf16_f32 v100, v104, v105
	v_cvt_pk_bf16_f32 v101, v106, v107
	global_store_dwordx4 v[126:127], v[98:101], off offset:256
	s_and_saveexec_b64 s[58:59], s[6:7]
	s_cbranch_execz .LBB0_647
	v_lshl_add_u64 v[98:99], v[112:113], 2, s[16:17]
	s_waitcnt lgkmcnt(0)
	v_add_f32_e32 v96, v96, v97
	global_atomic_add_f32 v[98:99], v96, off
.LBB0_647:
	s_or_b64 exec, exec, s[58:59]
	v_or_b32_e32 v96, 32, v148
	s_waitcnt lgkmcnt(0)
	v_ashrrev_i32_e32 v97, 31, v96
	v_lshlrev_b64 v[106:107], 13, v[96:97]
	v_lshl_add_u64 v[98:99], s[52:53], 0, v[106:107]
	v_lshl_add_u64 v[108:109], v[98:99], 0, v[146:147]
	s_nop 1
	v_lshlrev_b64 v[110:111], 12, v[96:97]
	v_lshl_add_u64 v[106:107], s[0:1], 0, v[106:107]
	v_lshl_add_u64 v[110:111], s[14:15], 0, v[110:111]
	v_lshl_add_u64 v[106:107], v[106:107], 0, v[146:147]
	v_lshl_add_u64 v[110:111], v[144:145], 1, v[110:111]
	s_waitcnt vmcnt(14)
	v_pk_add_f32 v[94:95], v[94:95], v[186:187]
	v_pk_add_f32 v[92:93], v[92:93], v[184:185]
	v_pk_add_f32 v[90:91], v[90:91], v[190:191]
	v_pk_add_f32 v[88:89], v[88:89], v[188:189]
	global_store_dwordx4 v[106:107], v[92:95], off
	global_store_dwordx4 v[106:107], v[88:91], off offset:16
	v_cvt_pk_bf16_f32 v98, v92, v93
	v_cvt_pk_bf16_f32 v99, v94, v95
	v_cvt_pk_bf16_f32 v100, v88, v89
	v_cvt_pk_bf16_f32 v101, v90, v91
	global_store_dwordx4 v[110:111], v[98:101], off
	s_nop 1
	s_nop 0
	v_mul_f32_e32 v93, v93, v93
	v_mul_f32_e32 v95, v95, v95
	v_mul_f32_e32 v89, v89, v89
	v_fmac_f32_e32 v93, v92, v92
	v_fmac_f32_e32 v95, v94, v94
	v_mul_f32_e32 v91, v91, v91
	v_fmac_f32_e32 v89, v88, v88
	v_add_f32_e32 v88, v93, v95
	v_fmac_f32_e32 v91, v90, v90
	v_add_f32_e32 v88, v88, v89
	v_add_f32_e32 v92, v91, v88
	v_pk_add_f32 v[86:87], v[86:87], v[194:195]
	v_pk_add_f32 v[84:85], v[84:85], v[192:193]
	v_pk_add_f32 v[88:89], v[80:81], v[196:197]
	v_mul_f32_e32 v80, v85, v85
	v_mul_f32_e32 v81, v87, v87
	v_pk_add_f32 v[90:91], v[82:83], v[198:199]
	v_lshl_add_u64 v[216:217], v[216:217], 0, s[100:101]
	global_load_dwordx4 v[184:187], v[216:217], off
	global_load_dwordx4 v[188:191], v[216:217], off offset:16
	global_load_dwordx4 v[192:195], v[216:217], off offset:512
	global_load_dwordx4 v[196:199], v[216:217], off offset:528
	v_mul_f32_e32 v82, v89, v89
	v_fmac_f32_e32 v80, v84, v84
	v_fmac_f32_e32 v81, v86, v86
	v_mul_f32_e32 v83, v91, v91
	v_fmac_f32_e32 v82, v88, v88
	v_add_f32_e32 v80, v80, v81
	v_add_f32_e32 v80, v80, v82
	v_fmac_f32_e32 v83, v90, v90
	v_add_f32_e32 v80, v83, v80
	v_add_f32_e32 v80, v92, v80
	ds_bpermute_b32 v81, v176, v80
	global_store_dwordx4 v[106:107], v[84:87], off offset:512
	global_store_dwordx4 v[106:107], v[88:91], off offset:528
	v_cvt_pk_bf16_f32 v82, v84, v85
	v_cvt_pk_bf16_f32 v83, v86, v87
	s_waitcnt lgkmcnt(0)
	v_add_f32_e32 v80, v80, v81
	ds_bpermute_b32 v81, v177, v80
	v_cvt_pk_bf16_f32 v84, v88, v89
	v_cvt_pk_bf16_f32 v85, v90, v91
	global_store_dwordx4 v[110:111], v[82:85], off offset:256
	s_and_saveexec_b64 s[58:59], s[6:7]
	s_cbranch_execz .LBB0_649
	v_lshl_add_u64 v[82:83], v[96:97], 2, s[16:17]
	s_waitcnt lgkmcnt(0)
	v_add_f32_e32 v80, v80, v81
	global_atomic_add_f32 v[82:83], v80, off
.LBB0_649:
	s_or_b64 exec, exec, s[58:59]
	v_or_b32_e32 v80, 48, v148
	s_waitcnt lgkmcnt(0)
	v_ashrrev_i32_e32 v81, 31, v80
	v_lshlrev_b64 v[90:91], 13, v[80:81]
	v_lshl_add_u64 v[82:83], s[52:53], 0, v[90:91]
	v_lshl_add_u64 v[92:93], v[82:83], 0, v[146:147]
	s_nop 1
	v_lshlrev_b64 v[94:95], 12, v[80:81]
	v_lshl_add_u64 v[90:91], s[0:1], 0, v[90:91]
	v_lshl_add_u64 v[94:95], s[14:15], 0, v[94:95]
	v_lshl_add_u64 v[90:91], v[90:91], 0, v[146:147]
	v_lshl_add_u64 v[94:95], v[144:145], 1, v[94:95]
	s_waitcnt vmcnt(14)
	v_pk_add_f32 v[78:79], v[78:79], v[202:203]
	v_pk_add_f32 v[76:77], v[76:77], v[200:201]
	v_pk_add_f32 v[74:75], v[74:75], v[206:207]
	v_pk_add_f32 v[72:73], v[72:73], v[204:205]
	global_store_dwordx4 v[90:91], v[76:79], off
	global_store_dwordx4 v[90:91], v[72:75], off offset:16
	v_cvt_pk_bf16_f32 v82, v76, v77
	v_cvt_pk_bf16_f32 v83, v78, v79
	v_cvt_pk_bf16_f32 v84, v72, v73
	v_cvt_pk_bf16_f32 v85, v74, v75
	global_store_dwordx4 v[94:95], v[82:85], off
	s_nop 1
	s_nop 0
	v_mul_f32_e32 v77, v77, v77
	v_mul_f32_e32 v79, v79, v79
	v_mul_f32_e32 v73, v73, v73
	v_fmac_f32_e32 v77, v76, v76
	v_fmac_f32_e32 v79, v78, v78
	v_mul_f32_e32 v75, v75, v75
	v_fmac_f32_e32 v73, v72, v72
	v_add_f32_e32 v72, v77, v79
	v_fmac_f32_e32 v75, v74, v74
	v_add_f32_e32 v72, v72, v73
	v_add_f32_e32 v76, v75, v72
	v_pk_add_f32 v[70:71], v[70:71], v[210:211]
	v_pk_add_f32 v[68:69], v[68:69], v[208:209]
	v_pk_add_f32 v[72:73], v[64:65], v[212:213]
	v_mul_f32_e32 v64, v69, v69
	v_mul_f32_e32 v65, v71, v71
	v_pk_add_f32 v[74:75], v[66:67], v[214:215]
	v_lshl_add_u64 v[216:217], v[216:217], 0, s[98:99]
	global_load_dwordx4 v[200:203], v[216:217], off
	global_load_dwordx4 v[204:207], v[216:217], off offset:16
	global_load_dwordx4 v[208:211], v[216:217], off offset:512
	global_load_dwordx4 v[212:215], v[216:217], off offset:528
	v_mul_f32_e32 v66, v73, v73
	v_fmac_f32_e32 v64, v68, v68
	v_fmac_f32_e32 v65, v70, v70
	v_mul_f32_e32 v67, v75, v75
	v_fmac_f32_e32 v66, v72, v72
	v_add_f32_e32 v64, v64, v65
	v_add_f32_e32 v64, v64, v66
	v_fmac_f32_e32 v67, v74, v74
	v_add_f32_e32 v64, v67, v64
	v_add_f32_e32 v64, v76, v64
	ds_bpermute_b32 v65, v176, v64
	global_store_dwordx4 v[90:91], v[68:71], off offset:512
	global_store_dwordx4 v[90:91], v[72:75], off offset:528
	v_cvt_pk_bf16_f32 v66, v68, v69
	v_cvt_pk_bf16_f32 v67, v70, v71
	s_waitcnt lgkmcnt(0)
	v_add_f32_e32 v64, v64, v65
	ds_bpermute_b32 v65, v177, v64
	v_cvt_pk_bf16_f32 v68, v72, v73
	v_cvt_pk_bf16_f32 v69, v74, v75
	global_store_dwordx4 v[94:95], v[66:69], off offset:256
	s_and_saveexec_b64 s[58:59], s[6:7]
	s_cbranch_execz .LBB0_651
	v_lshl_add_u64 v[66:67], v[80:81], 2, s[16:17]
	s_waitcnt lgkmcnt(0)
	v_add_f32_e32 v64, v64, v65
	global_atomic_add_f32 v[66:67], v64, off
.LBB0_651:
	s_or_b64 exec, exec, s[58:59]
	v_or_b32_e32 v64, 0x80, v148
	s_waitcnt lgkmcnt(0)
	v_ashrrev_i32_e32 v65, 31, v64
	v_lshlrev_b64 v[74:75], 13, v[64:65]
	v_lshl_add_u64 v[66:67], s[52:53], 0, v[74:75]
	v_lshl_add_u64 v[76:77], v[66:67], 0, v[146:147]
	s_nop 1
	v_lshlrev_b64 v[78:79], 12, v[64:65]
	v_lshl_add_u64 v[74:75], s[0:1], 0, v[74:75]
	v_lshl_add_u64 v[78:79], s[14:15], 0, v[78:79]
	v_lshl_add_u64 v[74:75], v[74:75], 0, v[146:147]
	v_lshl_add_u64 v[78:79], v[144:145], 1, v[78:79]
	s_waitcnt vmcnt(14)
	v_pk_add_f32 v[62:63], v[62:63], v[186:187]
	v_pk_add_f32 v[60:61], v[60:61], v[184:185]
	v_pk_add_f32 v[58:59], v[58:59], v[190:191]
	v_pk_add_f32 v[56:57], v[56:57], v[188:189]
	global_store_dwordx4 v[74:75], v[60:63], off
	global_store_dwordx4 v[74:75], v[56:59], off offset:16
	v_cvt_pk_bf16_f32 v66, v60, v61
	v_cvt_pk_bf16_f32 v67, v62, v63
	v_cvt_pk_bf16_f32 v68, v56, v57
	v_cvt_pk_bf16_f32 v69, v58, v59
	global_store_dwordx4 v[78:79], v[66:69], off
	s_nop 1
	s_nop 0
	v_mul_f32_e32 v61, v61, v61
	v_mul_f32_e32 v63, v63, v63
	v_mul_f32_e32 v57, v57, v57
	v_fmac_f32_e32 v61, v60, v60
	v_fmac_f32_e32 v63, v62, v62
	v_mul_f32_e32 v59, v59, v59
	v_fmac_f32_e32 v57, v56, v56
	v_add_f32_e32 v56, v61, v63
	v_fmac_f32_e32 v59, v58, v58
	v_add_f32_e32 v56, v56, v57
	v_add_f32_e32 v60, v59, v56
	v_pk_add_f32 v[54:55], v[54:55], v[194:195]
	v_pk_add_f32 v[52:53], v[52:53], v[192:193]
	v_pk_add_f32 v[56:57], v[48:49], v[196:197]
	v_mul_f32_e32 v48, v53, v53
	v_mul_f32_e32 v49, v55, v55
	v_pk_add_f32 v[58:59], v[50:51], v[198:199]
	v_lshl_add_u64 v[216:217], v[216:217], 0, s[98:99]
	global_load_dwordx4 v[184:187], v[216:217], off
	global_load_dwordx4 v[188:191], v[216:217], off offset:16
	global_load_dwordx4 v[192:195], v[216:217], off offset:512
	global_load_dwordx4 v[196:199], v[216:217], off offset:528
	v_mul_f32_e32 v50, v57, v57
	v_fmac_f32_e32 v48, v52, v52
	v_fmac_f32_e32 v49, v54, v54
	v_mul_f32_e32 v51, v59, v59
	v_fmac_f32_e32 v50, v56, v56
	v_add_f32_e32 v48, v48, v49
	v_add_f32_e32 v48, v48, v50
	v_fmac_f32_e32 v51, v58, v58
	v_add_f32_e32 v48, v51, v48
	v_add_f32_e32 v48, v60, v48
	ds_bpermute_b32 v49, v176, v48
	global_store_dwordx4 v[74:75], v[52:55], off offset:512
	global_store_dwordx4 v[74:75], v[56:59], off offset:528
	v_cvt_pk_bf16_f32 v50, v52, v53
	v_cvt_pk_bf16_f32 v51, v54, v55
	s_waitcnt lgkmcnt(0)
	v_add_f32_e32 v48, v48, v49
	ds_bpermute_b32 v49, v177, v48
	v_cvt_pk_bf16_f32 v52, v56, v57
	v_cvt_pk_bf16_f32 v53, v58, v59
	global_store_dwordx4 v[78:79], v[50:53], off offset:256
	s_and_saveexec_b64 s[58:59], s[6:7]
	s_cbranch_execz .LBB0_653
	v_lshl_add_u64 v[50:51], v[64:65], 2, s[16:17]
	s_waitcnt lgkmcnt(0)
	v_add_f32_e32 v48, v48, v49
	global_atomic_add_f32 v[50:51], v48, off
.LBB0_653:
	s_or_b64 exec, exec, s[58:59]
	v_or_b32_e32 v48, 0x90, v148
	s_waitcnt lgkmcnt(0)
	v_ashrrev_i32_e32 v49, 31, v48
	v_lshlrev_b64 v[58:59], 13, v[48:49]
	v_lshl_add_u64 v[50:51], s[52:53], 0, v[58:59]
	v_lshl_add_u64 v[60:61], v[50:51], 0, v[146:147]
	s_nop 1
	v_lshlrev_b64 v[62:63], 12, v[48:49]
	v_lshl_add_u64 v[58:59], s[0:1], 0, v[58:59]
	v_lshl_add_u64 v[62:63], s[14:15], 0, v[62:63]
	v_lshl_add_u64 v[58:59], v[58:59], 0, v[146:147]
	v_lshl_add_u64 v[62:63], v[144:145], 1, v[62:63]
	s_waitcnt vmcnt(14)
	v_pk_add_f32 v[46:47], v[46:47], v[202:203]
	v_pk_add_f32 v[44:45], v[44:45], v[200:201]
	v_pk_add_f32 v[42:43], v[42:43], v[206:207]
	v_pk_add_f32 v[40:41], v[40:41], v[204:205]
	global_store_dwordx4 v[58:59], v[44:47], off
	global_store_dwordx4 v[58:59], v[40:43], off offset:16
	v_cvt_pk_bf16_f32 v50, v44, v45
	v_cvt_pk_bf16_f32 v51, v46, v47
	v_cvt_pk_bf16_f32 v52, v40, v41
	v_cvt_pk_bf16_f32 v53, v42, v43
	global_store_dwordx4 v[62:63], v[50:53], off
	s_nop 1
	s_nop 0
	v_mul_f32_e32 v45, v45, v45
	v_mul_f32_e32 v47, v47, v47
	v_mul_f32_e32 v41, v41, v41
	v_fmac_f32_e32 v45, v44, v44
	v_fmac_f32_e32 v47, v46, v46
	v_mul_f32_e32 v43, v43, v43
	v_fmac_f32_e32 v41, v40, v40
	v_add_f32_e32 v40, v45, v47
	v_fmac_f32_e32 v43, v42, v42
	v_add_f32_e32 v40, v40, v41
	v_add_f32_e32 v44, v43, v40
	v_pk_add_f32 v[38:39], v[38:39], v[210:211]
	v_pk_add_f32 v[36:37], v[36:37], v[208:209]
	v_pk_add_f32 v[40:41], v[32:33], v[212:213]
	v_mul_f32_e32 v32, v37, v37
	v_mul_f32_e32 v33, v39, v39
	v_pk_add_f32 v[42:43], v[34:35], v[214:215]
	v_lshl_add_u64 v[216:217], v[216:217], 0, s[98:99]
	global_load_dwordx4 v[200:203], v[216:217], off
	global_load_dwordx4 v[204:207], v[216:217], off offset:16
	global_load_dwordx4 v[208:211], v[216:217], off offset:512
	global_load_dwordx4 v[212:215], v[216:217], off offset:528
	v_mul_f32_e32 v34, v41, v41
	v_fmac_f32_e32 v32, v36, v36
	v_fmac_f32_e32 v33, v38, v38
	v_mul_f32_e32 v35, v43, v43
	v_fmac_f32_e32 v34, v40, v40
	v_add_f32_e32 v32, v32, v33
	v_add_f32_e32 v32, v32, v34
	v_fmac_f32_e32 v35, v42, v42
	v_add_f32_e32 v32, v35, v32
	v_add_f32_e32 v32, v44, v32
	ds_bpermute_b32 v33, v176, v32
	global_store_dwordx4 v[58:59], v[36:39], off offset:512
	global_store_dwordx4 v[58:59], v[40:43], off offset:528
	v_cvt_pk_bf16_f32 v34, v36, v37
	v_cvt_pk_bf16_f32 v35, v38, v39
	s_waitcnt lgkmcnt(0)
	v_add_f32_e32 v32, v32, v33
	ds_bpermute_b32 v33, v177, v32
	v_cvt_pk_bf16_f32 v36, v40, v41
	v_cvt_pk_bf16_f32 v37, v42, v43
	global_store_dwordx4 v[62:63], v[34:37], off offset:256
	s_and_saveexec_b64 s[58:59], s[6:7]
	s_cbranch_execz .LBB0_655
	v_lshl_add_u64 v[34:35], v[48:49], 2, s[16:17]
	s_waitcnt lgkmcnt(0)
	v_add_f32_e32 v32, v32, v33
	global_atomic_add_f32 v[34:35], v32, off
.LBB0_655:
	s_or_b64 exec, exec, s[58:59]
	v_or_b32_e32 v32, 0xa0, v148
	s_waitcnt lgkmcnt(0)
	v_ashrrev_i32_e32 v33, 31, v32
	v_lshlrev_b64 v[42:43], 13, v[32:33]
	v_lshl_add_u64 v[34:35], s[52:53], 0, v[42:43]
	v_lshl_add_u64 v[44:45], v[34:35], 0, v[146:147]
	s_nop 1
	v_lshlrev_b64 v[46:47], 12, v[32:33]
	v_lshl_add_u64 v[42:43], s[0:1], 0, v[42:43]
	v_lshl_add_u64 v[46:47], s[14:15], 0, v[46:47]
	v_lshl_add_u64 v[42:43], v[42:43], 0, v[146:147]
	v_lshl_add_u64 v[46:47], v[144:145], 1, v[46:47]
	s_waitcnt vmcnt(14)
	v_pk_add_f32 v[30:31], v[30:31], v[186:187]
	v_pk_add_f32 v[28:29], v[28:29], v[184:185]
	v_pk_add_f32 v[26:27], v[26:27], v[190:191]
	v_pk_add_f32 v[24:25], v[24:25], v[188:189]
	global_store_dwordx4 v[42:43], v[28:31], off
	global_store_dwordx4 v[42:43], v[24:27], off offset:16
	v_cvt_pk_bf16_f32 v34, v28, v29
	v_cvt_pk_bf16_f32 v35, v30, v31
	v_cvt_pk_bf16_f32 v36, v24, v25
	v_cvt_pk_bf16_f32 v37, v26, v27
	global_store_dwordx4 v[46:47], v[34:37], off
	s_nop 1
	s_nop 0
	v_mul_f32_e32 v29, v29, v29
	v_mul_f32_e32 v31, v31, v31
	v_mul_f32_e32 v25, v25, v25
	v_fmac_f32_e32 v29, v28, v28
	v_fmac_f32_e32 v31, v30, v30
	v_mul_f32_e32 v27, v27, v27
	v_fmac_f32_e32 v25, v24, v24
	v_add_f32_e32 v24, v29, v31
	v_fmac_f32_e32 v27, v26, v26
	v_add_f32_e32 v24, v24, v25
	v_add_f32_e32 v28, v27, v24
	v_pk_add_f32 v[22:23], v[22:23], v[194:195]
	v_pk_add_f32 v[20:21], v[20:21], v[192:193]
	v_pk_add_f32 v[24:25], v[16:17], v[196:197]
	v_mul_f32_e32 v16, v21, v21
	v_mul_f32_e32 v17, v23, v23
	v_pk_add_f32 v[26:27], v[18:19], v[198:199]
	v_mul_f32_e32 v18, v25, v25
	v_fmac_f32_e32 v16, v20, v20
	v_fmac_f32_e32 v17, v22, v22
	v_mul_f32_e32 v19, v27, v27
	v_fmac_f32_e32 v18, v24, v24
	v_add_f32_e32 v16, v16, v17
	v_add_f32_e32 v16, v16, v18
	v_fmac_f32_e32 v19, v26, v26
	v_add_f32_e32 v16, v19, v16
	v_add_f32_e32 v16, v28, v16
	ds_bpermute_b32 v17, v176, v16
	global_store_dwordx4 v[42:43], v[20:23], off offset:512
	global_store_dwordx4 v[42:43], v[24:27], off offset:528
	v_cvt_pk_bf16_f32 v18, v20, v21
	v_cvt_pk_bf16_f32 v19, v22, v23
	s_waitcnt lgkmcnt(0)
	v_add_f32_e32 v16, v16, v17
	ds_bpermute_b32 v17, v177, v16
	v_cvt_pk_bf16_f32 v20, v24, v25
	v_cvt_pk_bf16_f32 v21, v26, v27
	global_store_dwordx4 v[46:47], v[18:21], off offset:256
	s_and_saveexec_b64 s[58:59], s[6:7]
	s_cbranch_execz .LBB0_657
	v_lshl_add_u64 v[18:19], v[32:33], 2, s[16:17]
	s_waitcnt lgkmcnt(0)
	v_add_f32_e32 v16, v16, v17
	global_atomic_add_f32 v[18:19], v16, off
.LBB0_657:
	s_or_b64 exec, exec, s[58:59]
	v_or_b32_e32 v16, 0xb0, v148
	s_waitcnt lgkmcnt(0)
	v_ashrrev_i32_e32 v17, 31, v16
	v_lshlrev_b64 v[26:27], 13, v[16:17]
	v_lshl_add_u64 v[18:19], s[52:53], 0, v[26:27]
	v_lshl_add_u64 v[28:29], v[18:19], 0, v[146:147]
	s_nop 1
	v_lshlrev_b64 v[30:31], 12, v[16:17]
	v_lshl_add_u64 v[26:27], s[0:1], 0, v[26:27]
	v_lshl_add_u64 v[30:31], s[14:15], 0, v[30:31]
	v_lshl_add_u64 v[26:27], v[26:27], 0, v[146:147]
	v_lshl_add_u64 v[30:31], v[144:145], 1, v[30:31]
	s_waitcnt vmcnt(10)
	v_pk_add_f32 v[14:15], v[14:15], v[202:203]
	v_pk_add_f32 v[12:13], v[12:13], v[200:201]
	v_pk_add_f32 v[10:11], v[10:11], v[206:207]
	v_pk_add_f32 v[8:9], v[8:9], v[204:205]
	global_store_dwordx4 v[26:27], v[12:15], off
	global_store_dwordx4 v[26:27], v[8:11], off offset:16
	v_cvt_pk_bf16_f32 v18, v12, v13
	v_cvt_pk_bf16_f32 v19, v14, v15
	v_cvt_pk_bf16_f32 v20, v8, v9
	v_cvt_pk_bf16_f32 v21, v10, v11
	global_store_dwordx4 v[30:31], v[18:21], off
	s_nop 1
	s_nop 0
	v_mul_f32_e32 v13, v13, v13
	v_mul_f32_e32 v15, v15, v15
	v_mul_f32_e32 v9, v9, v9
	v_fmac_f32_e32 v13, v12, v12
	v_fmac_f32_e32 v15, v14, v14
	v_mul_f32_e32 v11, v11, v11
	v_fmac_f32_e32 v9, v8, v8
	v_add_f32_e32 v8, v13, v15
	v_fmac_f32_e32 v11, v10, v10
	v_add_f32_e32 v8, v8, v9
	v_add_f32_e32 v12, v11, v8
	v_pk_add_f32 v[6:7], v[6:7], v[210:211]
	v_pk_add_f32 v[4:5], v[4:5], v[208:209]
	v_pk_add_f32 v[8:9], v[0:1], v[212:213]
	v_mul_f32_e32 v0, v5, v5
	v_mul_f32_e32 v1, v7, v7
	v_pk_add_f32 v[10:11], v[2:3], v[214:215]
	v_mul_f32_e32 v2, v9, v9
	v_fmac_f32_e32 v0, v4, v4
	v_fmac_f32_e32 v1, v6, v6
	v_mul_f32_e32 v3, v11, v11
	v_fmac_f32_e32 v2, v8, v8
	v_add_f32_e32 v0, v0, v1
	v_add_f32_e32 v0, v0, v2
	v_fmac_f32_e32 v3, v10, v10
	v_add_f32_e32 v0, v3, v0
	v_add_f32_e32 v0, v12, v0
	ds_bpermute_b32 v1, v176, v0
	global_store_dwordx4 v[26:27], v[4:7], off offset:512
	global_store_dwordx4 v[26:27], v[8:11], off offset:528
	v_cvt_pk_bf16_f32 v2, v4, v5
	v_cvt_pk_bf16_f32 v3, v6, v7
	s_waitcnt lgkmcnt(0)
	v_add_f32_e32 v0, v0, v1
	ds_bpermute_b32 v1, v177, v0
	v_cvt_pk_bf16_f32 v4, v8, v9
	v_cvt_pk_bf16_f32 v5, v10, v11
	global_store_dwordx4 v[30:31], v[2:5], off offset:256
	s_and_saveexec_b64 s[58:59], s[6:7]
	s_cbranch_execz .LBB0_659
	v_lshl_add_u64 v[2:3], v[16:17], 2, s[16:17]
	s_waitcnt lgkmcnt(0)
	v_add_f32_e32 v0, v0, v1
	global_atomic_add_f32 v[2:3], v0, off

.LBB0_813:
	v_lshl_or_b32 v148, s60, 8, v151
	v_lshl_or_b32 v144, s62, 8, v152
	v_ashrrev_i32_e32 v149, 31, v148
	v_lshlrev_b64 v[168:169], 13, v[148:149]
	v_ashrrev_i32_e32 v145, 31, v144
	v_lshl_add_u64 v[160:161], s[0:1], 0, v[168:169]
	v_lshlrev_b64 v[146:147], 2, v[144:145]
	v_lshl_add_u64 v[170:171], v[160:161], 0, v[146:147]
	s_mov_b32 s98, 0x20000
	s_mov_b32 s99, 0
	s_mov_b32 s100, 0xa0000
	s_mov_b32 s101, 0
	global_load_dwordx4 v[184:187], v[170:171], off
	global_load_dwordx4 v[188:191], v[170:171], off offset:16
	global_load_dwordx4 v[192:195], v[170:171], off offset:512
	global_load_dwordx4 v[196:199], v[170:171], off offset:528
	v_lshl_add_u64 v[216:217], v[170:171], 0, s[98:99]
	global_load_dwordx4 v[200:203], v[216:217], off
	global_load_dwordx4 v[204:207], v[216:217], off offset:16
	global_load_dwordx4 v[208:211], v[216:217], off offset:512
	global_load_dwordx4 v[212:215], v[216:217], off offset:528
	s_nop 1
	v_lshlrev_b64 v[172:173], 12, v[148:149]
	v_lshl_add_u64 v[168:169], s[10:11], 0, v[168:169]
	v_lshl_add_u64 v[172:173], s[16:17], 0, v[172:173]
	v_lshl_add_u64 v[168:169], v[168:169], 0, v[146:147]
	v_lshl_add_u64 v[172:173], v[144:145], 1, v[172:173]
	s_waitcnt vmcnt(3)
	v_pk_add_f32 v[126:127], v[126:127], v[186:187]
	v_pk_add_f32 v[124:125], v[124:125], v[184:185]
	v_pk_add_f32 v[122:123], v[122:123], v[190:191]
	v_pk_add_f32 v[120:121], v[120:121], v[188:189]
	global_store_dwordx4 v[168:169], v[124:127], off
	global_store_dwordx4 v[168:169], v[120:123], off offset:16
	v_cvt_pk_bf16_f32 v160, v124, v125
	v_cvt_pk_bf16_f32 v161, v126, v127
	v_cvt_pk_bf16_f32 v162, v120, v121
	v_cvt_pk_bf16_f32 v163, v122, v123
	global_store_dwordx4 v[172:173], v[160:163], off
	s_nop 1
	s_nop 0
	v_mul_f32_e32 v125, v125, v125
	v_mul_f32_e32 v127, v127, v127
	v_mul_f32_e32 v121, v121, v121
	v_fmac_f32_e32 v125, v124, v124
	v_fmac_f32_e32 v127, v126, v126
	v_mul_f32_e32 v123, v123, v123
	v_fmac_f32_e32 v121, v120, v120
	v_add_f32_e32 v120, v125, v127
	v_fmac_f32_e32 v123, v122, v122
	v_add_f32_e32 v120, v120, v121
	v_add_f32_e32 v124, v123, v120
	v_pk_add_f32 v[118:119], v[118:119], v[194:195]
	v_pk_add_f32 v[116:117], v[116:117], v[192:193]
	v_pk_add_f32 v[120:121], v[112:113], v[196:197]
	v_mul_f32_e32 v112, v117, v117
	v_mul_f32_e32 v113, v119, v119
	v_pk_add_f32 v[122:123], v[114:115], v[198:199]
	v_lshl_add_u64 v[216:217], v[216:217], 0, s[98:99]
	global_load_dwordx4 v[184:187], v[216:217], off
	global_load_dwordx4 v[188:191], v[216:217], off offset:16
	global_load_dwordx4 v[192:195], v[216:217], off offset:512
	global_load_dwordx4 v[196:199], v[216:217], off offset:528
	v_mul_f32_e32 v114, v121, v121
	v_fmac_f32_e32 v112, v116, v116
	v_fmac_f32_e32 v113, v118, v118
	v_mul_f32_e32 v115, v123, v123
	v_fmac_f32_e32 v114, v120, v120
	v_add_f32_e32 v112, v112, v113
	v_add_f32_e32 v112, v112, v114
	v_fmac_f32_e32 v115, v122, v122
	v_add_f32_e32 v112, v115, v112
	v_add_f32_e32 v112, v124, v112
	ds_bpermute_b32 v113, v176, v112
	global_store_dwordx4 v[168:169], v[116:119], off offset:512
	global_store_dwordx4 v[168:169], v[120:123], off offset:528
	v_cvt_pk_bf16_f32 v114, v116, v117
	v_cvt_pk_bf16_f32 v115, v118, v119
	s_waitcnt lgkmcnt(0)
	v_add_f32_e32 v112, v112, v113
	ds_bpermute_b32 v113, v177, v112
	v_cvt_pk_bf16_f32 v116, v120, v121
	v_cvt_pk_bf16_f32 v117, v122, v123
	global_store_dwordx4 v[172:173], v[114:117], off offset:256
	s_and_saveexec_b64 s[60:61], s[6:7]
	s_cbranch_execz .LBB0_815
	v_lshl_add_u64 v[114:115], v[148:149], 2, s[46:47]
	s_waitcnt lgkmcnt(0)
	v_add_f32_e32 v112, v112, v113
	global_atomic_add_f32 v[114:115], v112, off
.LBB0_815:
	s_or_b64 exec, exec, s[60:61]
	v_or_b32_e32 v112, 16, v148
	s_waitcnt lgkmcnt(0)
	v_ashrrev_i32_e32 v113, 31, v112
	v_lshlrev_b64 v[122:123], 13, v[112:113]
	v_lshl_add_u64 v[114:115], s[0:1], 0, v[122:123]
	v_lshl_add_u64 v[124:125], v[114:115], 0, v[146:147]
	s_nop 1
	v_lshlrev_b64 v[126:127], 12, v[112:113]
	v_lshl_add_u64 v[122:123], s[10:11], 0, v[122:123]
	v_lshl_add_u64 v[126:127], s[16:17], 0, v[126:127]
	v_lshl_add_u64 v[122:123], v[122:123], 0, v[146:147]
	v_lshl_add_u64 v[126:127], v[144:145], 1, v[126:127]
	s_waitcnt vmcnt(10)
	v_pk_add_f32 v[110:111], v[110:111], v[202:203]
	v_pk_add_f32 v[108:109], v[108:109], v[200:201]
	v_pk_add_f32 v[106:107], v[106:107], v[206:207]
	v_pk_add_f32 v[104:105], v[104:105], v[204:205]
	global_store_dwordx4 v[122:123], v[108:111], off
	global_store_dwordx4 v[122:123], v[104:107], off offset:16
	v_cvt_pk_bf16_f32 v114, v108, v109
	v_cvt_pk_bf16_f32 v115, v110, v111
	v_cvt_pk_bf16_f32 v116, v104, v105
	v_cvt_pk_bf16_f32 v117, v106, v107
	global_store_dwordx4 v[126:127], v[114:117], off
	s_nop 1
	s_nop 0
	v_mul_f32_e32 v109, v109, v109
	v_mul_f32_e32 v111, v111, v111
	v_mul_f32_e32 v105, v105, v105
	v_fmac_f32_e32 v109, v108, v108
	v_fmac_f32_e32 v111, v110, v110
	v_mul_f32_e32 v107, v107, v107
	v_fmac_f32_e32 v105, v104, v104
	v_add_f32_e32 v104, v109, v111
	v_fmac_f32_e32 v107, v106, v106
	v_add_f32_e32 v104, v104, v105
	v_add_f32_e32 v108, v107, v104
	v_pk_add_f32 v[102:103], v[102:103], v[210:211]
	v_pk_add_f32 v[100:101], v[100:101], v[208:209]
	v_pk_add_f32 v[104:105], v[96:97], v[212:213]
	v_mul_f32_e32 v96, v101, v101
	v_mul_f32_e32 v97, v103, v103
	v_pk_add_f32 v[106:107], v[98:99], v[214:215]
	v_lshl_add_u64 v[216:217], v[216:217], 0, s[98:99]
	global_load_dwordx4 v[200:203], v[216:217], off
	global_load_dwordx4 v[204:207], v[216:217], off offset:16
	global_load_dwordx4 v[208:211], v[216:217], off offset:512
	global_load_dwordx4 v[212:215], v[216:217], off offset:528
	v_mul_f32_e32 v98, v105, v105
	v_fmac_f32_e32 v96, v100, v100
	v_fmac_f32_e32 v97, v102, v102
	v_mul_f32_e32 v99, v107, v107
	v_fmac_f32_e32 v98, v104, v104
	v_add_f32_e32 v96, v96, v97
	v_add_f32_e32 v96, v96, v98
	v_fmac_f32_e32 v99, v106, v106
	v_add_f32_e32 v96, v99, v96
	v_add_f32_e32 v96, v108, v96
	ds_bpermute_b32 v97, v176, v96
	global_store_dwordx4 v[122:123], v[100:103], off offset:512
	global_store_dwordx4 v[122:123], v[104:107], off offset:528
	v_cvt_pk_bf16_f32 v98, v100, v101
	v_cvt_pk_bf16_f32 v99, v102, v103
	s_waitcnt lgkmcnt(0)
	v_add_f32_e32 v96, v96, v97
	ds_bpermute_b32 v97, v177, v96
	v_cvt_pk_bf16_f32 v100, v104, v105
	v_cvt_pk_bf16_f32 v101, v106, v107
	global_store_dwordx4 v[126:127], v[98:101], off offset:256
	s_and_saveexec_b64 s[60:61], s[6:7]
	s_cbranch_execz .LBB0_817
	v_lshl_add_u64 v[98:99], v[112:113], 2, s[46:47]
	s_waitcnt lgkmcnt(0)
	v_add_f32_e32 v96, v96, v97
	global_atomic_add_f32 v[98:99], v96, off
.LBB0_817:
	s_or_b64 exec, exec, s[60:61]
	v_or_b32_e32 v96, 32, v148
	s_waitcnt lgkmcnt(0)
	v_ashrrev_i32_e32 v97, 31, v96
	v_lshlrev_b64 v[106:107], 13, v[96:97]
	v_lshl_add_u64 v[98:99], s[0:1], 0, v[106:107]
	v_lshl_add_u64 v[108:109], v[98:99], 0, v[146:147]
	s_nop 1
	v_lshlrev_b64 v[110:111], 12, v[96:97]
	v_lshl_add_u64 v[106:107], s[10:11], 0, v[106:107]
	v_lshl_add_u64 v[110:111], s[16:17], 0, v[110:111]
	v_lshl_add_u64 v[106:107], v[106:107], 0, v[146:147]
	v_lshl_add_u64 v[110:111], v[144:145], 1, v[110:111]
	s_waitcnt vmcnt(14)
	v_pk_add_f32 v[94:95], v[94:95], v[186:187]
	v_pk_add_f32 v[92:93], v[92:93], v[184:185]
	v_pk_add_f32 v[90:91], v[90:91], v[190:191]
	v_pk_add_f32 v[88:89], v[88:89], v[188:189]
	global_store_dwordx4 v[106:107], v[92:95], off
	global_store_dwordx4 v[106:107], v[88:91], off offset:16
	v_cvt_pk_bf16_f32 v98, v92, v93
	v_cvt_pk_bf16_f32 v99, v94, v95
	v_cvt_pk_bf16_f32 v100, v88, v89
	v_cvt_pk_bf16_f32 v101, v90, v91
	global_store_dwordx4 v[110:111], v[98:101], off
	s_nop 1
	s_nop 0
	v_mul_f32_e32 v93, v93, v93
	v_mul_f32_e32 v95, v95, v95
	v_mul_f32_e32 v89, v89, v89
	v_fmac_f32_e32 v93, v92, v92
	v_fmac_f32_e32 v95, v94, v94
	v_mul_f32_e32 v91, v91, v91
	v_fmac_f32_e32 v89, v88, v88
	v_add_f32_e32 v88, v93, v95
	v_fmac_f32_e32 v91, v90, v90
	v_add_f32_e32 v88, v88, v89
	v_add_f32_e32 v92, v91, v88
	v_pk_add_f32 v[86:87], v[86:87], v[194:195]
	v_pk_add_f32 v[84:85], v[84:85], v[192:193]
	v_pk_add_f32 v[88:89], v[80:81], v[196:197]
	v_mul_f32_e32 v80, v85, v85
	v_mul_f32_e32 v81, v87, v87
	v_pk_add_f32 v[90:91], v[82:83], v[198:199]
	v_lshl_add_u64 v[216:217], v[216:217], 0, s[100:101]
	global_load_dwordx4 v[184:187], v[216:217], off
	global_load_dwordx4 v[188:191], v[216:217], off offset:16
	global_load_dwordx4 v[192:195], v[216:217], off offset:512
	global_load_dwordx4 v[196:199], v[216:217], off offset:528
	v_mul_f32_e32 v82, v89, v89
	v_fmac_f32_e32 v80, v84, v84
	v_fmac_f32_e32 v81, v86, v86
	v_mul_f32_e32 v83, v91, v91
	v_fmac_f32_e32 v82, v88, v88
	v_add_f32_e32 v80, v80, v81
	v_add_f32_e32 v80, v80, v82
	v_fmac_f32_e32 v83, v90, v90
	v_add_f32_e32 v80, v83, v80
	v_add_f32_e32 v80, v92, v80
	ds_bpermute_b32 v81, v176, v80
	global_store_dwordx4 v[106:107], v[84:87], off offset:512
	global_store_dwordx4 v[106:107], v[88:91], off offset:528
	v_cvt_pk_bf16_f32 v82, v84, v85
	v_cvt_pk_bf16_f32 v83, v86, v87
	s_waitcnt lgkmcnt(0)
	v_add_f32_e32 v80, v80, v81
	ds_bpermute_b32 v81, v177, v80
	v_cvt_pk_bf16_f32 v84, v88, v89
	v_cvt_pk_bf16_f32 v85, v90, v91
	global_store_dwordx4 v[110:111], v[82:85], off offset:256
	s_and_saveexec_b64 s[60:61], s[6:7]
	s_cbranch_execz .LBB0_819
	v_lshl_add_u64 v[82:83], v[96:97], 2, s[46:47]
	s_waitcnt lgkmcnt(0)
	v_add_f32_e32 v80, v80, v81
	global_atomic_add_f32 v[82:83], v80, off
.LBB0_819:
	s_or_b64 exec, exec, s[60:61]
	v_or_b32_e32 v80, 48, v148
	s_waitcnt lgkmcnt(0)
	v_ashrrev_i32_e32 v81, 31, v80
	v_lshlrev_b64 v[90:91], 13, v[80:81]
	v_lshl_add_u64 v[82:83], s[0:1], 0, v[90:91]
	v_lshl_add_u64 v[92:93], v[82:83], 0, v[146:147]
	s_nop 1
	v_lshlrev_b64 v[94:95], 12, v[80:81]
	v_lshl_add_u64 v[90:91], s[10:11], 0, v[90:91]
	v_lshl_add_u64 v[94:95], s[16:17], 0, v[94:95]
	v_lshl_add_u64 v[90:91], v[90:91], 0, v[146:147]
	v_lshl_add_u64 v[94:95], v[144:145], 1, v[94:95]
	s_waitcnt vmcnt(14)
	v_pk_add_f32 v[78:79], v[78:79], v[202:203]
	v_pk_add_f32 v[76:77], v[76:77], v[200:201]
	v_pk_add_f32 v[74:75], v[74:75], v[206:207]
	v_pk_add_f32 v[72:73], v[72:73], v[204:205]
	global_store_dwordx4 v[90:91], v[76:79], off
	global_store_dwordx4 v[90:91], v[72:75], off offset:16
	v_cvt_pk_bf16_f32 v82, v76, v77
	v_cvt_pk_bf16_f32 v83, v78, v79
	v_cvt_pk_bf16_f32 v84, v72, v73
	v_cvt_pk_bf16_f32 v85, v74, v75
	global_store_dwordx4 v[94:95], v[82:85], off
	s_nop 1
	s_nop 0
	v_mul_f32_e32 v77, v77, v77
	v_mul_f32_e32 v79, v79, v79
	v_mul_f32_e32 v73, v73, v73
	v_fmac_f32_e32 v77, v76, v76
	v_fmac_f32_e32 v79, v78, v78
	v_mul_f32_e32 v75, v75, v75
	v_fmac_f32_e32 v73, v72, v72
	v_add_f32_e32 v72, v77, v79
	v_fmac_f32_e32 v75, v74, v74
	v_add_f32_e32 v72, v72, v73
	v_add_f32_e32 v76, v75, v72
	v_pk_add_f32 v[70:71], v[70:71], v[210:211]
	v_pk_add_f32 v[68:69], v[68:69], v[208:209]
	v_pk_add_f32 v[72:73], v[64:65], v[212:213]
	v_mul_f32_e32 v64, v69, v69
	v_mul_f32_e32 v65, v71, v71
	v_pk_add_f32 v[74:75], v[66:67], v[214:215]
	v_lshl_add_u64 v[216:217], v[216:217], 0, s[98:99]
	global_load_dwordx4 v[200:203], v[216:217], off
	global_load_dwordx4 v[204:207], v[216:217], off offset:16
	global_load_dwordx4 v[208:211], v[216:217], off offset:512
	global_load_dwordx4 v[212:215], v[216:217], off offset:528
	v_mul_f32_e32 v66, v73, v73
	v_fmac_f32_e32 v64, v68, v68
	v_fmac_f32_e32 v65, v70, v70
	v_mul_f32_e32 v67, v75, v75
	v_fmac_f32_e32 v66, v72, v72
	v_add_f32_e32 v64, v64, v65
	v_add_f32_e32 v64, v64, v66
	v_fmac_f32_e32 v67, v74, v74
	v_add_f32_e32 v64, v67, v64
	v_add_f32_e32 v64, v76, v64
	ds_bpermute_b32 v65, v176, v64
	global_store_dwordx4 v[90:91], v[68:71], off offset:512
	global_store_dwordx4 v[90:91], v[72:75], off offset:528
	v_cvt_pk_bf16_f32 v66, v68, v69
	v_cvt_pk_bf16_f32 v67, v70, v71
	s_waitcnt lgkmcnt(0)
	v_add_f32_e32 v64, v64, v65
	ds_bpermute_b32 v65, v177, v64
	v_cvt_pk_bf16_f32 v68, v72, v73
	v_cvt_pk_bf16_f32 v69, v74, v75
	global_store_dwordx4 v[94:95], v[66:69], off offset:256
	s_and_saveexec_b64 s[60:61], s[6:7]
	s_cbranch_execz .LBB0_821
	v_lshl_add_u64 v[66:67], v[80:81], 2, s[46:47]
	s_waitcnt lgkmcnt(0)
	v_add_f32_e32 v64, v64, v65
	global_atomic_add_f32 v[66:67], v64, off
.LBB0_821:
	s_or_b64 exec, exec, s[60:61]
	v_or_b32_e32 v64, 0x80, v148
	s_waitcnt lgkmcnt(0)
	v_ashrrev_i32_e32 v65, 31, v64
	v_lshlrev_b64 v[74:75], 13, v[64:65]
	v_lshl_add_u64 v[66:67], s[0:1], 0, v[74:75]
	v_lshl_add_u64 v[76:77], v[66:67], 0, v[146:147]
	s_nop 1
	v_lshlrev_b64 v[78:79], 12, v[64:65]
	v_lshl_add_u64 v[74:75], s[10:11], 0, v[74:75]
	v_lshl_add_u64 v[78:79], s[16:17], 0, v[78:79]
	v_lshl_add_u64 v[74:75], v[74:75], 0, v[146:147]
	v_lshl_add_u64 v[78:79], v[144:145], 1, v[78:79]
	s_waitcnt vmcnt(14)
	v_pk_add_f32 v[62:63], v[62:63], v[186:187]
	v_pk_add_f32 v[60:61], v[60:61], v[184:185]
	v_pk_add_f32 v[58:59], v[58:59], v[190:191]
	v_pk_add_f32 v[56:57], v[56:57], v[188:189]
	global_store_dwordx4 v[74:75], v[60:63], off
	global_store_dwordx4 v[74:75], v[56:59], off offset:16
	v_cvt_pk_bf16_f32 v66, v60, v61
	v_cvt_pk_bf16_f32 v67, v62, v63
	v_cvt_pk_bf16_f32 v68, v56, v57
	v_cvt_pk_bf16_f32 v69, v58, v59
	global_store_dwordx4 v[78:79], v[66:69], off
	s_nop 1
	s_nop 0
	v_mul_f32_e32 v61, v61, v61
	v_mul_f32_e32 v63, v63, v63
	v_mul_f32_e32 v57, v57, v57
	v_fmac_f32_e32 v61, v60, v60
	v_fmac_f32_e32 v63, v62, v62
	v_mul_f32_e32 v59, v59, v59
	v_fmac_f32_e32 v57, v56, v56
	v_add_f32_e32 v56, v61, v63
	v_fmac_f32_e32 v59, v58, v58
	v_add_f32_e32 v56, v56, v57
	v_add_f32_e32 v60, v59, v56
	v_pk_add_f32 v[54:55], v[54:55], v[194:195]
	v_pk_add_f32 v[52:53], v[52:53], v[192:193]
	v_pk_add_f32 v[56:57], v[48:49], v[196:197]
	v_mul_f32_e32 v48, v53, v53
	v_mul_f32_e32 v49, v55, v55
	v_pk_add_f32 v[58:59], v[50:51], v[198:199]
	v_lshl_add_u64 v[216:217], v[216:217], 0, s[98:99]
	global_load_dwordx4 v[184:187], v[216:217], off
	global_load_dwordx4 v[188:191], v[216:217], off offset:16
	global_load_dwordx4 v[192:195], v[216:217], off offset:512
	global_load_dwordx4 v[196:199], v[216:217], off offset:528
	v_mul_f32_e32 v50, v57, v57
	v_fmac_f32_e32 v48, v52, v52
	v_fmac_f32_e32 v49, v54, v54
	v_mul_f32_e32 v51, v59, v59
	v_fmac_f32_e32 v50, v56, v56
	v_add_f32_e32 v48, v48, v49
	v_add_f32_e32 v48, v48, v50
	v_fmac_f32_e32 v51, v58, v58
	v_add_f32_e32 v48, v51, v48
	v_add_f32_e32 v48, v60, v48
	ds_bpermute_b32 v49, v176, v48
	global_store_dwordx4 v[74:75], v[52:55], off offset:512
	global_store_dwordx4 v[74:75], v[56:59], off offset:528
	v_cvt_pk_bf16_f32 v50, v52, v53
	v_cvt_pk_bf16_f32 v51, v54, v55
	s_waitcnt lgkmcnt(0)
	v_add_f32_e32 v48, v48, v49
	ds_bpermute_b32 v49, v177, v48
	v_cvt_pk_bf16_f32 v52, v56, v57
	v_cvt_pk_bf16_f32 v53, v58, v59
	global_store_dwordx4 v[78:79], v[50:53], off offset:256
	s_and_saveexec_b64 s[60:61], s[6:7]
	s_cbranch_execz .LBB0_823
	v_lshl_add_u64 v[50:51], v[64:65], 2, s[46:47]
	s_waitcnt lgkmcnt(0)
	v_add_f32_e32 v48, v48, v49
	global_atomic_add_f32 v[50:51], v48, off
.LBB0_823:
	s_or_b64 exec, exec, s[60:61]
	v_or_b32_e32 v48, 0x90, v148
	s_waitcnt lgkmcnt(0)
	v_ashrrev_i32_e32 v49, 31, v48
	v_lshlrev_b64 v[58:59], 13, v[48:49]
	v_lshl_add_u64 v[50:51], s[0:1], 0, v[58:59]
	v_lshl_add_u64 v[60:61], v[50:51], 0, v[146:147]
	s_nop 1
	v_lshlrev_b64 v[62:63], 12, v[48:49]
	v_lshl_add_u64 v[58:59], s[10:11], 0, v[58:59]
	v_lshl_add_u64 v[62:63], s[16:17], 0, v[62:63]
	v_lshl_add_u64 v[58:59], v[58:59], 0, v[146:147]
	v_lshl_add_u64 v[62:63], v[144:145], 1, v[62:63]
	s_waitcnt vmcnt(14)
	v_pk_add_f32 v[46:47], v[46:47], v[202:203]
	v_pk_add_f32 v[44:45], v[44:45], v[200:201]
	v_pk_add_f32 v[42:43], v[42:43], v[206:207]
	v_pk_add_f32 v[40:41], v[40:41], v[204:205]
	global_store_dwordx4 v[58:59], v[44:47], off
	global_store_dwordx4 v[58:59], v[40:43], off offset:16
	v_cvt_pk_bf16_f32 v50, v44, v45
	v_cvt_pk_bf16_f32 v51, v46, v47
	v_cvt_pk_bf16_f32 v52, v40, v41
	v_cvt_pk_bf16_f32 v53, v42, v43
	global_store_dwordx4 v[62:63], v[50:53], off
	s_nop 1
	s_nop 0
	v_mul_f32_e32 v45, v45, v45
	v_mul_f32_e32 v47, v47, v47
	v_mul_f32_e32 v41, v41, v41
	v_fmac_f32_e32 v45, v44, v44
	v_fmac_f32_e32 v47, v46, v46
	v_mul_f32_e32 v43, v43, v43
	v_fmac_f32_e32 v41, v40, v40
	v_add_f32_e32 v40, v45, v47
	v_fmac_f32_e32 v43, v42, v42
	v_add_f32_e32 v40, v40, v41
	v_add_f32_e32 v44, v43, v40
	v_pk_add_f32 v[38:39], v[38:39], v[210:211]
	v_pk_add_f32 v[36:37], v[36:37], v[208:209]
	v_pk_add_f32 v[40:41], v[32:33], v[212:213]
	v_mul_f32_e32 v32, v37, v37
	v_mul_f32_e32 v33, v39, v39
	v_pk_add_f32 v[42:43], v[34:35], v[214:215]
	v_lshl_add_u64 v[216:217], v[216:217], 0, s[98:99]
	global_load_dwordx4 v[200:203], v[216:217], off
	global_load_dwordx4 v[204:207], v[216:217], off offset:16
	global_load_dwordx4 v[208:211], v[216:217], off offset:512
	global_load_dwordx4 v[212:215], v[216:217], off offset:528
	v_mul_f32_e32 v34, v41, v41
	v_fmac_f32_e32 v32, v36, v36
	v_fmac_f32_e32 v33, v38, v38
	v_mul_f32_e32 v35, v43, v43
	v_fmac_f32_e32 v34, v40, v40
	v_add_f32_e32 v32, v32, v33
	v_add_f32_e32 v32, v32, v34
	v_fmac_f32_e32 v35, v42, v42
	v_add_f32_e32 v32, v35, v32
	v_add_f32_e32 v32, v44, v32
	ds_bpermute_b32 v33, v176, v32
	global_store_dwordx4 v[58:59], v[36:39], off offset:512
	global_store_dwordx4 v[58:59], v[40:43], off offset:528
	v_cvt_pk_bf16_f32 v34, v36, v37
	v_cvt_pk_bf16_f32 v35, v38, v39
	s_waitcnt lgkmcnt(0)
	v_add_f32_e32 v32, v32, v33
	ds_bpermute_b32 v33, v177, v32
	v_cvt_pk_bf16_f32 v36, v40, v41
	v_cvt_pk_bf16_f32 v37, v42, v43
	global_store_dwordx4 v[62:63], v[34:37], off offset:256
	s_and_saveexec_b64 s[60:61], s[6:7]
	s_cbranch_execz .LBB0_825
	v_lshl_add_u64 v[34:35], v[48:49], 2, s[46:47]
	s_waitcnt lgkmcnt(0)
	v_add_f32_e32 v32, v32, v33
	global_atomic_add_f32 v[34:35], v32, off
.LBB0_825:
	s_or_b64 exec, exec, s[60:61]
	v_or_b32_e32 v32, 0xa0, v148
	s_waitcnt lgkmcnt(0)
	v_ashrrev_i32_e32 v33, 31, v32
	v_lshlrev_b64 v[42:43], 13, v[32:33]
	v_lshl_add_u64 v[34:35], s[0:1], 0, v[42:43]
	v_lshl_add_u64 v[44:45], v[34:35], 0, v[146:147]
	s_nop 1
	v_lshlrev_b64 v[46:47], 12, v[32:33]
	v_lshl_add_u64 v[42:43], s[10:11], 0, v[42:43]
	v_lshl_add_u64 v[46:47], s[16:17], 0, v[46:47]
	v_lshl_add_u64 v[42:43], v[42:43], 0, v[146:147]
	v_lshl_add_u64 v[46:47], v[144:145], 1, v[46:47]
	s_waitcnt vmcnt(14)
	v_pk_add_f32 v[30:31], v[30:31], v[186:187]
	v_pk_add_f32 v[28:29], v[28:29], v[184:185]
	v_pk_add_f32 v[26:27], v[26:27], v[190:191]
	v_pk_add_f32 v[24:25], v[24:25], v[188:189]
	global_store_dwordx4 v[42:43], v[28:31], off
	global_store_dwordx4 v[42:43], v[24:27], off offset:16
	v_cvt_pk_bf16_f32 v34, v28, v29
	v_cvt_pk_bf16_f32 v35, v30, v31
	v_cvt_pk_bf16_f32 v36, v24, v25
	v_cvt_pk_bf16_f32 v37, v26, v27
	global_store_dwordx4 v[46:47], v[34:37], off
	s_nop 1
	s_nop 0
	v_mul_f32_e32 v29, v29, v29
	v_mul_f32_e32 v31, v31, v31
	v_mul_f32_e32 v25, v25, v25
	v_fmac_f32_e32 v29, v28, v28
	v_fmac_f32_e32 v31, v30, v30
	v_mul_f32_e32 v27, v27, v27
	v_fmac_f32_e32 v25, v24, v24
	v_add_f32_e32 v24, v29, v31
	v_fmac_f32_e32 v27, v26, v26
	v_add_f32_e32 v24, v24, v25
	v_add_f32_e32 v28, v27, v24
	v_pk_add_f32 v[22:23], v[22:23], v[194:195]
	v_pk_add_f32 v[20:21], v[20:21], v[192:193]
	v_pk_add_f32 v[24:25], v[16:17], v[196:197]
	v_mul_f32_e32 v16, v21, v21
	v_mul_f32_e32 v17, v23, v23
	v_pk_add_f32 v[26:27], v[18:19], v[198:199]
	v_mul_f32_e32 v18, v25, v25
	v_fmac_f32_e32 v16, v20, v20
	v_fmac_f32_e32 v17, v22, v22
	v_mul_f32_e32 v19, v27, v27
	v_fmac_f32_e32 v18, v24, v24
	v_add_f32_e32 v16, v16, v17
	v_add_f32_e32 v16, v16, v18
	v_fmac_f32_e32 v19, v26, v26
	v_add_f32_e32 v16, v19, v16
	v_add_f32_e32 v16, v28, v16
	ds_bpermute_b32 v17, v176, v16
	global_store_dwordx4 v[42:43], v[20:23], off offset:512
	global_store_dwordx4 v[42:43], v[24:27], off offset:528
	v_cvt_pk_bf16_f32 v18, v20, v21
	v_cvt_pk_bf16_f32 v19, v22, v23
	s_waitcnt lgkmcnt(0)
	v_add_f32_e32 v16, v16, v17
	ds_bpermute_b32 v17, v177, v16
	v_cvt_pk_bf16_f32 v20, v24, v25
	v_cvt_pk_bf16_f32 v21, v26, v27
	global_store_dwordx4 v[46:47], v[18:21], off offset:256
	s_and_saveexec_b64 s[60:61], s[6:7]
	s_cbranch_execz .LBB0_827
	v_lshl_add_u64 v[18:19], v[32:33], 2, s[46:47]
	s_waitcnt lgkmcnt(0)
	v_add_f32_e32 v16, v16, v17
	global_atomic_add_f32 v[18:19], v16, off
.LBB0_827:
	s_or_b64 exec, exec, s[60:61]
	v_or_b32_e32 v16, 0xb0, v148
	s_waitcnt lgkmcnt(0)
	v_ashrrev_i32_e32 v17, 31, v16
	v_lshlrev_b64 v[26:27], 13, v[16:17]
	v_lshl_add_u64 v[18:19], s[0:1], 0, v[26:27]
	v_lshl_add_u64 v[28:29], v[18:19], 0, v[146:147]
	s_nop 1
	v_lshlrev_b64 v[30:31], 12, v[16:17]
	v_lshl_add_u64 v[26:27], s[10:11], 0, v[26:27]
	v_lshl_add_u64 v[30:31], s[16:17], 0, v[30:31]
	v_lshl_add_u64 v[26:27], v[26:27], 0, v[146:147]
	v_lshl_add_u64 v[30:31], v[144:145], 1, v[30:31]
	s_waitcnt vmcnt(10)
	v_pk_add_f32 v[14:15], v[14:15], v[202:203]
	v_pk_add_f32 v[12:13], v[12:13], v[200:201]
	v_pk_add_f32 v[10:11], v[10:11], v[206:207]
	v_pk_add_f32 v[8:9], v[8:9], v[204:205]
	global_store_dwordx4 v[26:27], v[12:15], off
	global_store_dwordx4 v[26:27], v[8:11], off offset:16
	v_cvt_pk_bf16_f32 v18, v12, v13
	v_cvt_pk_bf16_f32 v19, v14, v15
	v_cvt_pk_bf16_f32 v20, v8, v9
	v_cvt_pk_bf16_f32 v21, v10, v11
	global_store_dwordx4 v[30:31], v[18:21], off
	s_nop 1
	s_nop 0
	v_mul_f32_e32 v13, v13, v13
	v_mul_f32_e32 v15, v15, v15
	v_mul_f32_e32 v9, v9, v9
	v_fmac_f32_e32 v13, v12, v12
	v_fmac_f32_e32 v15, v14, v14
	v_mul_f32_e32 v11, v11, v11
	v_fmac_f32_e32 v9, v8, v8
	v_add_f32_e32 v8, v13, v15
	v_fmac_f32_e32 v11, v10, v10
	v_add_f32_e32 v8, v8, v9
	v_add_f32_e32 v12, v11, v8
	v_pk_add_f32 v[6:7], v[6:7], v[210:211]
	v_pk_add_f32 v[4:5], v[4:5], v[208:209]
	v_pk_add_f32 v[8:9], v[0:1], v[212:213]
	v_mul_f32_e32 v0, v5, v5
	v_mul_f32_e32 v1, v7, v7
	v_pk_add_f32 v[10:11], v[2:3], v[214:215]
	v_mul_f32_e32 v2, v9, v9
	v_fmac_f32_e32 v0, v4, v4
	v_fmac_f32_e32 v1, v6, v6
	v_mul_f32_e32 v3, v11, v11
	v_fmac_f32_e32 v2, v8, v8
	v_add_f32_e32 v0, v0, v1
	v_add_f32_e32 v0, v0, v2
	v_fmac_f32_e32 v3, v10, v10
	v_add_f32_e32 v0, v3, v0
	v_add_f32_e32 v0, v12, v0
	ds_bpermute_b32 v1, v176, v0
	global_store_dwordx4 v[26:27], v[4:7], off offset:512
	global_store_dwordx4 v[26:27], v[8:11], off offset:528
	v_cvt_pk_bf16_f32 v2, v4, v5
	v_cvt_pk_bf16_f32 v3, v6, v7
	s_waitcnt lgkmcnt(0)
	v_add_f32_e32 v0, v0, v1
	ds_bpermute_b32 v1, v177, v0
	v_cvt_pk_bf16_f32 v4, v8, v9
	v_cvt_pk_bf16_f32 v5, v10, v11
	global_store_dwordx4 v[30:31], v[2:5], off offset:256
	s_and_saveexec_b64 s[60:61], s[6:7]
	s_cbranch_execz .LBB0_829
	v_lshl_add_u64 v[2:3], v[16:17], 2, s[46:47]
	s_waitcnt lgkmcnt(0)
	v_add_f32_e32 v0, v0, v1
	global_atomic_add_f32 v[2:3], v0, off

.LBB0_1432:
	v_lshl_or_b32 v148, s50, 8, v151
	v_lshl_or_b32 v144, s52, 8, v152
	v_ashrrev_i32_e32 v149, 31, v148
	v_lshlrev_b64 v[164:165], 13, v[148:149]
	v_ashrrev_i32_e32 v145, 31, v144
	v_lshl_add_u64 v[156:157], s[0:1], 0, v[164:165]
	v_lshlrev_b64 v[146:147], 2, v[144:145]
	v_lshl_add_u64 v[166:167], v[156:157], 0, v[146:147]
	s_mov_b32 s98, 0x20000
	s_mov_b32 s99, 0
	s_mov_b32 s100, 0xa0000
	s_mov_b32 s101, 0
	global_load_dwordx4 v[184:187], v[166:167], off
	global_load_dwordx4 v[188:191], v[166:167], off offset:16
	global_load_dwordx4 v[192:195], v[166:167], off offset:512
	global_load_dwordx4 v[196:199], v[166:167], off offset:528
	v_lshl_add_u64 v[216:217], v[166:167], 0, s[98:99]
	global_load_dwordx4 v[200:203], v[216:217], off
	global_load_dwordx4 v[204:207], v[216:217], off offset:16
	global_load_dwordx4 v[208:211], v[216:217], off offset:512
	global_load_dwordx4 v[212:215], v[216:217], off offset:528
	s_nop 1
	v_lshlrev_b64 v[168:169], 12, v[148:149]
	v_lshl_add_u64 v[164:165], s[10:11], 0, v[164:165]
	v_lshl_add_u64 v[168:169], s[16:17], 0, v[168:169]
	v_lshl_add_u64 v[164:165], v[164:165], 0, v[146:147]
	v_lshl_add_u64 v[168:169], v[144:145], 1, v[168:169]
	s_waitcnt vmcnt(3)
	v_pk_add_f32 v[126:127], v[126:127], v[186:187]
	v_pk_add_f32 v[124:125], v[124:125], v[184:185]
	v_pk_add_f32 v[122:123], v[122:123], v[190:191]
	v_pk_add_f32 v[120:121], v[120:121], v[188:189]
	global_store_dwordx4 v[164:165], v[124:127], off
	global_store_dwordx4 v[164:165], v[120:123], off offset:16
	v_cvt_pk_bf16_f32 v156, v124, v125
	v_cvt_pk_bf16_f32 v157, v126, v127
	v_cvt_pk_bf16_f32 v158, v120, v121
	v_cvt_pk_bf16_f32 v159, v122, v123
	global_store_dwordx4 v[168:169], v[156:159], off
	s_nop 1
	s_nop 0
	v_mul_f32_e32 v125, v125, v125
	v_mul_f32_e32 v127, v127, v127
	v_mul_f32_e32 v121, v121, v121
	v_fmac_f32_e32 v125, v124, v124
	v_fmac_f32_e32 v127, v126, v126
	v_mul_f32_e32 v123, v123, v123
	v_fmac_f32_e32 v121, v120, v120
	v_add_f32_e32 v120, v125, v127
	v_fmac_f32_e32 v123, v122, v122
	v_add_f32_e32 v120, v120, v121
	v_add_f32_e32 v124, v123, v120
	v_pk_add_f32 v[118:119], v[118:119], v[194:195]
	v_pk_add_f32 v[116:117], v[116:117], v[192:193]
	v_pk_add_f32 v[120:121], v[112:113], v[196:197]
	v_mul_f32_e32 v112, v117, v117
	v_mul_f32_e32 v113, v119, v119
	v_pk_add_f32 v[122:123], v[114:115], v[198:199]
	v_lshl_add_u64 v[216:217], v[216:217], 0, s[98:99]
	global_load_dwordx4 v[184:187], v[216:217], off
	global_load_dwordx4 v[188:191], v[216:217], off offset:16
	global_load_dwordx4 v[192:195], v[216:217], off offset:512
	global_load_dwordx4 v[196:199], v[216:217], off offset:528
	v_mul_f32_e32 v114, v121, v121
	v_fmac_f32_e32 v112, v116, v116
	v_fmac_f32_e32 v113, v118, v118
	v_mul_f32_e32 v115, v123, v123
	v_fmac_f32_e32 v114, v120, v120
	v_add_f32_e32 v112, v112, v113
	v_add_f32_e32 v112, v112, v114
	v_fmac_f32_e32 v115, v122, v122
	v_add_f32_e32 v112, v115, v112
	v_add_f32_e32 v112, v124, v112
	ds_bpermute_b32 v113, v176, v112
	global_store_dwordx4 v[164:165], v[116:119], off offset:512
	global_store_dwordx4 v[164:165], v[120:123], off offset:528
	v_cvt_pk_bf16_f32 v114, v116, v117
	v_cvt_pk_bf16_f32 v115, v118, v119
	s_waitcnt lgkmcnt(0)
	v_add_f32_e32 v112, v112, v113
	ds_bpermute_b32 v113, v177, v112
	v_cvt_pk_bf16_f32 v116, v120, v121
	v_cvt_pk_bf16_f32 v117, v122, v123
	global_store_dwordx4 v[168:169], v[114:117], off offset:256
	s_and_saveexec_b64 s[50:51], s[6:7]
	s_cbranch_execz .LBB0_1434
	v_lshl_add_u64 v[114:115], v[148:149], 2, s[38:39]
	s_waitcnt lgkmcnt(0)
	v_add_f32_e32 v112, v112, v113
	global_atomic_add_f32 v[114:115], v112, off
.LBB0_1434:
	s_or_b64 exec, exec, s[50:51]
	v_or_b32_e32 v112, 16, v148
	s_waitcnt lgkmcnt(0)
	v_ashrrev_i32_e32 v113, 31, v112
	v_lshlrev_b64 v[122:123], 13, v[112:113]
	v_lshl_add_u64 v[114:115], s[0:1], 0, v[122:123]
	v_lshl_add_u64 v[124:125], v[114:115], 0, v[146:147]
	s_nop 1
	v_lshlrev_b64 v[126:127], 12, v[112:113]
	v_lshl_add_u64 v[122:123], s[10:11], 0, v[122:123]
	v_lshl_add_u64 v[126:127], s[16:17], 0, v[126:127]
	v_lshl_add_u64 v[122:123], v[122:123], 0, v[146:147]
	v_lshl_add_u64 v[126:127], v[144:145], 1, v[126:127]
	s_waitcnt vmcnt(10)
	v_pk_add_f32 v[110:111], v[110:111], v[202:203]
	v_pk_add_f32 v[108:109], v[108:109], v[200:201]
	v_pk_add_f32 v[106:107], v[106:107], v[206:207]
	v_pk_add_f32 v[104:105], v[104:105], v[204:205]
	global_store_dwordx4 v[122:123], v[108:111], off
	global_store_dwordx4 v[122:123], v[104:107], off offset:16
	v_cvt_pk_bf16_f32 v114, v108, v109
	v_cvt_pk_bf16_f32 v115, v110, v111
	v_cvt_pk_bf16_f32 v116, v104, v105
	v_cvt_pk_bf16_f32 v117, v106, v107
	global_store_dwordx4 v[126:127], v[114:117], off
	s_nop 1
	s_nop 0
	v_mul_f32_e32 v109, v109, v109
	v_mul_f32_e32 v111, v111, v111
	v_mul_f32_e32 v105, v105, v105
	v_fmac_f32_e32 v109, v108, v108
	v_fmac_f32_e32 v111, v110, v110
	v_mul_f32_e32 v107, v107, v107
	v_fmac_f32_e32 v105, v104, v104
	v_add_f32_e32 v104, v109, v111
	v_fmac_f32_e32 v107, v106, v106
	v_add_f32_e32 v104, v104, v105
	v_add_f32_e32 v108, v107, v104
	v_pk_add_f32 v[102:103], v[102:103], v[210:211]
	v_pk_add_f32 v[100:101], v[100:101], v[208:209]
	v_pk_add_f32 v[104:105], v[96:97], v[212:213]
	v_mul_f32_e32 v96, v101, v101
	v_mul_f32_e32 v97, v103, v103
	v_pk_add_f32 v[106:107], v[98:99], v[214:215]
	v_lshl_add_u64 v[216:217], v[216:217], 0, s[98:99]
	global_load_dwordx4 v[200:203], v[216:217], off
	global_load_dwordx4 v[204:207], v[216:217], off offset:16
	global_load_dwordx4 v[208:211], v[216:217], off offset:512
	global_load_dwordx4 v[212:215], v[216:217], off offset:528
	v_mul_f32_e32 v98, v105, v105
	v_fmac_f32_e32 v96, v100, v100
	v_fmac_f32_e32 v97, v102, v102
	v_mul_f32_e32 v99, v107, v107
	v_fmac_f32_e32 v98, v104, v104
	v_add_f32_e32 v96, v96, v97
	v_add_f32_e32 v96, v96, v98
	v_fmac_f32_e32 v99, v106, v106
	v_add_f32_e32 v96, v99, v96
	v_add_f32_e32 v96, v108, v96
	ds_bpermute_b32 v97, v176, v96
	global_store_dwordx4 v[122:123], v[100:103], off offset:512
	global_store_dwordx4 v[122:123], v[104:107], off offset:528
	v_cvt_pk_bf16_f32 v98, v100, v101
	v_cvt_pk_bf16_f32 v99, v102, v103
	s_waitcnt lgkmcnt(0)
	v_add_f32_e32 v96, v96, v97
	ds_bpermute_b32 v97, v177, v96
	v_cvt_pk_bf16_f32 v100, v104, v105
	v_cvt_pk_bf16_f32 v101, v106, v107
	global_store_dwordx4 v[126:127], v[98:101], off offset:256
	s_and_saveexec_b64 s[50:51], s[6:7]
	s_cbranch_execz .LBB0_1436
	v_lshl_add_u64 v[98:99], v[112:113], 2, s[38:39]
	s_waitcnt lgkmcnt(0)
	v_add_f32_e32 v96, v96, v97
	global_atomic_add_f32 v[98:99], v96, off
.LBB0_1436:
	s_or_b64 exec, exec, s[50:51]
	v_or_b32_e32 v96, 32, v148
	s_waitcnt lgkmcnt(0)
	v_ashrrev_i32_e32 v97, 31, v96
	v_lshlrev_b64 v[106:107], 13, v[96:97]
	v_lshl_add_u64 v[98:99], s[0:1], 0, v[106:107]
	v_lshl_add_u64 v[108:109], v[98:99], 0, v[146:147]
	s_nop 1
	v_lshlrev_b64 v[110:111], 12, v[96:97]
	v_lshl_add_u64 v[106:107], s[10:11], 0, v[106:107]
	v_lshl_add_u64 v[110:111], s[16:17], 0, v[110:111]
	v_lshl_add_u64 v[106:107], v[106:107], 0, v[146:147]
	v_lshl_add_u64 v[110:111], v[144:145], 1, v[110:111]
	s_waitcnt vmcnt(14)
	v_pk_add_f32 v[94:95], v[94:95], v[186:187]
	v_pk_add_f32 v[92:93], v[92:93], v[184:185]
	v_pk_add_f32 v[90:91], v[90:91], v[190:191]
	v_pk_add_f32 v[88:89], v[88:89], v[188:189]
	global_store_dwordx4 v[106:107], v[92:95], off
	global_store_dwordx4 v[106:107], v[88:91], off offset:16
	v_cvt_pk_bf16_f32 v98, v92, v93
	v_cvt_pk_bf16_f32 v99, v94, v95
	v_cvt_pk_bf16_f32 v100, v88, v89
	v_cvt_pk_bf16_f32 v101, v90, v91
	global_store_dwordx4 v[110:111], v[98:101], off
	s_nop 1
	s_nop 0
	v_mul_f32_e32 v93, v93, v93
	v_mul_f32_e32 v95, v95, v95
	v_mul_f32_e32 v89, v89, v89
	v_fmac_f32_e32 v93, v92, v92
	v_fmac_f32_e32 v95, v94, v94
	v_mul_f32_e32 v91, v91, v91
	v_fmac_f32_e32 v89, v88, v88
	v_add_f32_e32 v88, v93, v95
	v_fmac_f32_e32 v91, v90, v90
	v_add_f32_e32 v88, v88, v89
	v_add_f32_e32 v92, v91, v88
	v_pk_add_f32 v[86:87], v[86:87], v[194:195]
	v_pk_add_f32 v[84:85], v[84:85], v[192:193]
	v_pk_add_f32 v[88:89], v[80:81], v[196:197]
	v_mul_f32_e32 v80, v85, v85
	v_mul_f32_e32 v81, v87, v87
	v_pk_add_f32 v[90:91], v[82:83], v[198:199]
	v_lshl_add_u64 v[216:217], v[216:217], 0, s[100:101]
	global_load_dwordx4 v[184:187], v[216:217], off
	global_load_dwordx4 v[188:191], v[216:217], off offset:16
	global_load_dwordx4 v[192:195], v[216:217], off offset:512
	global_load_dwordx4 v[196:199], v[216:217], off offset:528
	v_mul_f32_e32 v82, v89, v89
	v_fmac_f32_e32 v80, v84, v84
	v_fmac_f32_e32 v81, v86, v86
	v_mul_f32_e32 v83, v91, v91
	v_fmac_f32_e32 v82, v88, v88
	v_add_f32_e32 v80, v80, v81
	v_add_f32_e32 v80, v80, v82
	v_fmac_f32_e32 v83, v90, v90
	v_add_f32_e32 v80, v83, v80
	v_add_f32_e32 v80, v92, v80
	ds_bpermute_b32 v81, v176, v80
	global_store_dwordx4 v[106:107], v[84:87], off offset:512
	global_store_dwordx4 v[106:107], v[88:91], off offset:528
	v_cvt_pk_bf16_f32 v82, v84, v85
	v_cvt_pk_bf16_f32 v83, v86, v87
	s_waitcnt lgkmcnt(0)
	v_add_f32_e32 v80, v80, v81
	ds_bpermute_b32 v81, v177, v80
	v_cvt_pk_bf16_f32 v84, v88, v89
	v_cvt_pk_bf16_f32 v85, v90, v91
	global_store_dwordx4 v[110:111], v[82:85], off offset:256
	s_and_saveexec_b64 s[50:51], s[6:7]
	s_cbranch_execz .LBB0_1438
	v_lshl_add_u64 v[82:83], v[96:97], 2, s[38:39]
	s_waitcnt lgkmcnt(0)
	v_add_f32_e32 v80, v80, v81
	global_atomic_add_f32 v[82:83], v80, off
.LBB0_1438:
	s_or_b64 exec, exec, s[50:51]
	v_or_b32_e32 v80, 48, v148
	s_waitcnt lgkmcnt(0)
	v_ashrrev_i32_e32 v81, 31, v80
	v_lshlrev_b64 v[90:91], 13, v[80:81]
	v_lshl_add_u64 v[82:83], s[0:1], 0, v[90:91]
	v_lshl_add_u64 v[92:93], v[82:83], 0, v[146:147]
	s_nop 1
	v_lshlrev_b64 v[94:95], 12, v[80:81]
	v_lshl_add_u64 v[90:91], s[10:11], 0, v[90:91]
	v_lshl_add_u64 v[94:95], s[16:17], 0, v[94:95]
	v_lshl_add_u64 v[90:91], v[90:91], 0, v[146:147]
	v_lshl_add_u64 v[94:95], v[144:145], 1, v[94:95]
	s_waitcnt vmcnt(14)
	v_pk_add_f32 v[78:79], v[78:79], v[202:203]
	v_pk_add_f32 v[76:77], v[76:77], v[200:201]
	v_pk_add_f32 v[74:75], v[74:75], v[206:207]
	v_pk_add_f32 v[72:73], v[72:73], v[204:205]
	global_store_dwordx4 v[90:91], v[76:79], off
	global_store_dwordx4 v[90:91], v[72:75], off offset:16
	v_cvt_pk_bf16_f32 v82, v76, v77
	v_cvt_pk_bf16_f32 v83, v78, v79
	v_cvt_pk_bf16_f32 v84, v72, v73
	v_cvt_pk_bf16_f32 v85, v74, v75
	global_store_dwordx4 v[94:95], v[82:85], off
	s_nop 1
	s_nop 0
	v_mul_f32_e32 v77, v77, v77
	v_mul_f32_e32 v79, v79, v79
	v_mul_f32_e32 v73, v73, v73
	v_fmac_f32_e32 v77, v76, v76
	v_fmac_f32_e32 v79, v78, v78
	v_mul_f32_e32 v75, v75, v75
	v_fmac_f32_e32 v73, v72, v72
	v_add_f32_e32 v72, v77, v79
	v_fmac_f32_e32 v75, v74, v74
	v_add_f32_e32 v72, v72, v73
	v_add_f32_e32 v76, v75, v72
	v_pk_add_f32 v[70:71], v[70:71], v[210:211]
	v_pk_add_f32 v[68:69], v[68:69], v[208:209]
	v_pk_add_f32 v[72:73], v[64:65], v[212:213]
	v_mul_f32_e32 v64, v69, v69
	v_mul_f32_e32 v65, v71, v71
	v_pk_add_f32 v[74:75], v[66:67], v[214:215]
	v_lshl_add_u64 v[216:217], v[216:217], 0, s[98:99]
	global_load_dwordx4 v[200:203], v[216:217], off
	global_load_dwordx4 v[204:207], v[216:217], off offset:16
	global_load_dwordx4 v[208:211], v[216:217], off offset:512
	global_load_dwordx4 v[212:215], v[216:217], off offset:528
	v_mul_f32_e32 v66, v73, v73
	v_fmac_f32_e32 v64, v68, v68
	v_fmac_f32_e32 v65, v70, v70
	v_mul_f32_e32 v67, v75, v75
	v_fmac_f32_e32 v66, v72, v72
	v_add_f32_e32 v64, v64, v65
	v_add_f32_e32 v64, v64, v66
	v_fmac_f32_e32 v67, v74, v74
	v_add_f32_e32 v64, v67, v64
	v_add_f32_e32 v64, v76, v64
	ds_bpermute_b32 v65, v176, v64
	global_store_dwordx4 v[90:91], v[68:71], off offset:512
	global_store_dwordx4 v[90:91], v[72:75], off offset:528
	v_cvt_pk_bf16_f32 v66, v68, v69
	v_cvt_pk_bf16_f32 v67, v70, v71
	s_waitcnt lgkmcnt(0)
	v_add_f32_e32 v64, v64, v65
	ds_bpermute_b32 v65, v177, v64
	v_cvt_pk_bf16_f32 v68, v72, v73
	v_cvt_pk_bf16_f32 v69, v74, v75
	global_store_dwordx4 v[94:95], v[66:69], off offset:256
	s_and_saveexec_b64 s[50:51], s[6:7]
	s_cbranch_execz .LBB0_1440
	v_lshl_add_u64 v[66:67], v[80:81], 2, s[38:39]
	s_waitcnt lgkmcnt(0)
	v_add_f32_e32 v64, v64, v65
	global_atomic_add_f32 v[66:67], v64, off
.LBB0_1440:
	s_or_b64 exec, exec, s[50:51]
	v_or_b32_e32 v64, 0x80, v148
	s_waitcnt lgkmcnt(0)
	v_ashrrev_i32_e32 v65, 31, v64
	v_lshlrev_b64 v[74:75], 13, v[64:65]
	v_lshl_add_u64 v[66:67], s[0:1], 0, v[74:75]
	v_lshl_add_u64 v[76:77], v[66:67], 0, v[146:147]
	s_nop 1
	v_lshlrev_b64 v[78:79], 12, v[64:65]
	v_lshl_add_u64 v[74:75], s[10:11], 0, v[74:75]
	v_lshl_add_u64 v[78:79], s[16:17], 0, v[78:79]
	v_lshl_add_u64 v[74:75], v[74:75], 0, v[146:147]
	v_lshl_add_u64 v[78:79], v[144:145], 1, v[78:79]
	s_waitcnt vmcnt(14)
	v_pk_add_f32 v[62:63], v[62:63], v[186:187]
	v_pk_add_f32 v[60:61], v[60:61], v[184:185]
	v_pk_add_f32 v[58:59], v[58:59], v[190:191]
	v_pk_add_f32 v[56:57], v[56:57], v[188:189]
	global_store_dwordx4 v[74:75], v[60:63], off
	global_store_dwordx4 v[74:75], v[56:59], off offset:16
	v_cvt_pk_bf16_f32 v66, v60, v61
	v_cvt_pk_bf16_f32 v67, v62, v63
	v_cvt_pk_bf16_f32 v68, v56, v57
	v_cvt_pk_bf16_f32 v69, v58, v59
	global_store_dwordx4 v[78:79], v[66:69], off
	s_nop 1
	s_nop 0
	v_mul_f32_e32 v61, v61, v61
	v_mul_f32_e32 v63, v63, v63
	v_mul_f32_e32 v57, v57, v57
	v_fmac_f32_e32 v61, v60, v60
	v_fmac_f32_e32 v63, v62, v62
	v_mul_f32_e32 v59, v59, v59
	v_fmac_f32_e32 v57, v56, v56
	v_add_f32_e32 v56, v61, v63
	v_fmac_f32_e32 v59, v58, v58
	v_add_f32_e32 v56, v56, v57
	v_add_f32_e32 v60, v59, v56
	v_pk_add_f32 v[54:55], v[54:55], v[194:195]
	v_pk_add_f32 v[52:53], v[52:53], v[192:193]
	v_pk_add_f32 v[56:57], v[48:49], v[196:197]
	v_mul_f32_e32 v48, v53, v53
	v_mul_f32_e32 v49, v55, v55
	v_pk_add_f32 v[58:59], v[50:51], v[198:199]
	v_lshl_add_u64 v[216:217], v[216:217], 0, s[98:99]
	global_load_dwordx4 v[184:187], v[216:217], off
	global_load_dwordx4 v[188:191], v[216:217], off offset:16
	global_load_dwordx4 v[192:195], v[216:217], off offset:512
	global_load_dwordx4 v[196:199], v[216:217], off offset:528
	v_mul_f32_e32 v50, v57, v57
	v_fmac_f32_e32 v48, v52, v52
	v_fmac_f32_e32 v49, v54, v54
	v_mul_f32_e32 v51, v59, v59
	v_fmac_f32_e32 v50, v56, v56
	v_add_f32_e32 v48, v48, v49
	v_add_f32_e32 v48, v48, v50
	v_fmac_f32_e32 v51, v58, v58
	v_add_f32_e32 v48, v51, v48
	v_add_f32_e32 v48, v60, v48
	ds_bpermute_b32 v49, v176, v48
	global_store_dwordx4 v[74:75], v[52:55], off offset:512
	global_store_dwordx4 v[74:75], v[56:59], off offset:528
	v_cvt_pk_bf16_f32 v50, v52, v53
	v_cvt_pk_bf16_f32 v51, v54, v55
	s_waitcnt lgkmcnt(0)
	v_add_f32_e32 v48, v48, v49
	ds_bpermute_b32 v49, v177, v48
	v_cvt_pk_bf16_f32 v52, v56, v57
	v_cvt_pk_bf16_f32 v53, v58, v59
	global_store_dwordx4 v[78:79], v[50:53], off offset:256
	s_and_saveexec_b64 s[50:51], s[6:7]
	s_cbranch_execz .LBB0_1442
	v_lshl_add_u64 v[50:51], v[64:65], 2, s[38:39]
	s_waitcnt lgkmcnt(0)
	v_add_f32_e32 v48, v48, v49
	global_atomic_add_f32 v[50:51], v48, off
.LBB0_1442:
	s_or_b64 exec, exec, s[50:51]
	v_or_b32_e32 v48, 0x90, v148
	s_waitcnt lgkmcnt(0)
	v_ashrrev_i32_e32 v49, 31, v48
	v_lshlrev_b64 v[58:59], 13, v[48:49]
	v_lshl_add_u64 v[50:51], s[0:1], 0, v[58:59]
	v_lshl_add_u64 v[60:61], v[50:51], 0, v[146:147]
	s_nop 1
	v_lshlrev_b64 v[62:63], 12, v[48:49]
	v_lshl_add_u64 v[58:59], s[10:11], 0, v[58:59]
	v_lshl_add_u64 v[62:63], s[16:17], 0, v[62:63]
	v_lshl_add_u64 v[58:59], v[58:59], 0, v[146:147]
	v_lshl_add_u64 v[62:63], v[144:145], 1, v[62:63]
	s_waitcnt vmcnt(14)
	v_pk_add_f32 v[46:47], v[46:47], v[202:203]
	v_pk_add_f32 v[44:45], v[44:45], v[200:201]
	v_pk_add_f32 v[42:43], v[42:43], v[206:207]
	v_pk_add_f32 v[40:41], v[40:41], v[204:205]
	global_store_dwordx4 v[58:59], v[44:47], off
	global_store_dwordx4 v[58:59], v[40:43], off offset:16
	v_cvt_pk_bf16_f32 v50, v44, v45
	v_cvt_pk_bf16_f32 v51, v46, v47
	v_cvt_pk_bf16_f32 v52, v40, v41
	v_cvt_pk_bf16_f32 v53, v42, v43
	global_store_dwordx4 v[62:63], v[50:53], off
	s_nop 1
	s_nop 0
	v_mul_f32_e32 v45, v45, v45
	v_mul_f32_e32 v47, v47, v47
	v_mul_f32_e32 v41, v41, v41
	v_fmac_f32_e32 v45, v44, v44
	v_fmac_f32_e32 v47, v46, v46
	v_mul_f32_e32 v43, v43, v43
	v_fmac_f32_e32 v41, v40, v40
	v_add_f32_e32 v40, v45, v47
	v_fmac_f32_e32 v43, v42, v42
	v_add_f32_e32 v40, v40, v41
	v_add_f32_e32 v44, v43, v40
	v_pk_add_f32 v[38:39], v[38:39], v[210:211]
	v_pk_add_f32 v[36:37], v[36:37], v[208:209]
	v_pk_add_f32 v[40:41], v[32:33], v[212:213]
	v_mul_f32_e32 v32, v37, v37
	v_mul_f32_e32 v33, v39, v39
	v_pk_add_f32 v[42:43], v[34:35], v[214:215]
	v_lshl_add_u64 v[216:217], v[216:217], 0, s[98:99]
	global_load_dwordx4 v[200:203], v[216:217], off
	global_load_dwordx4 v[204:207], v[216:217], off offset:16
	global_load_dwordx4 v[208:211], v[216:217], off offset:512
	global_load_dwordx4 v[212:215], v[216:217], off offset:528
	v_mul_f32_e32 v34, v41, v41
	v_fmac_f32_e32 v32, v36, v36
	v_fmac_f32_e32 v33, v38, v38
	v_mul_f32_e32 v35, v43, v43
	v_fmac_f32_e32 v34, v40, v40
	v_add_f32_e32 v32, v32, v33
	v_add_f32_e32 v32, v32, v34
	v_fmac_f32_e32 v35, v42, v42
	v_add_f32_e32 v32, v35, v32
	v_add_f32_e32 v32, v44, v32
	ds_bpermute_b32 v33, v176, v32
	global_store_dwordx4 v[58:59], v[36:39], off offset:512
	global_store_dwordx4 v[58:59], v[40:43], off offset:528
	v_cvt_pk_bf16_f32 v34, v36, v37
	v_cvt_pk_bf16_f32 v35, v38, v39
	s_waitcnt lgkmcnt(0)
	v_add_f32_e32 v32, v32, v33
	ds_bpermute_b32 v33, v177, v32
	v_cvt_pk_bf16_f32 v36, v40, v41
	v_cvt_pk_bf16_f32 v37, v42, v43
	global_store_dwordx4 v[62:63], v[34:37], off offset:256
	s_and_saveexec_b64 s[50:51], s[6:7]
	s_cbranch_execz .LBB0_1444
	v_lshl_add_u64 v[34:35], v[48:49], 2, s[38:39]
	s_waitcnt lgkmcnt(0)
	v_add_f32_e32 v32, v32, v33
	global_atomic_add_f32 v[34:35], v32, off
.LBB0_1444:
	s_or_b64 exec, exec, s[50:51]
	v_or_b32_e32 v32, 0xa0, v148
	s_waitcnt lgkmcnt(0)
	v_ashrrev_i32_e32 v33, 31, v32
	v_lshlrev_b64 v[42:43], 13, v[32:33]
	v_lshl_add_u64 v[34:35], s[0:1], 0, v[42:43]
	v_lshl_add_u64 v[44:45], v[34:35], 0, v[146:147]
	s_nop 1
	v_lshlrev_b64 v[46:47], 12, v[32:33]
	v_lshl_add_u64 v[42:43], s[10:11], 0, v[42:43]
	v_lshl_add_u64 v[46:47], s[16:17], 0, v[46:47]
	v_lshl_add_u64 v[42:43], v[42:43], 0, v[146:147]
	v_lshl_add_u64 v[46:47], v[144:145], 1, v[46:47]
	s_waitcnt vmcnt(14)
	v_pk_add_f32 v[30:31], v[30:31], v[186:187]
	v_pk_add_f32 v[28:29], v[28:29], v[184:185]
	v_pk_add_f32 v[26:27], v[26:27], v[190:191]
	v_pk_add_f32 v[24:25], v[24:25], v[188:189]
	global_store_dwordx4 v[42:43], v[28:31], off
	global_store_dwordx4 v[42:43], v[24:27], off offset:16
	v_cvt_pk_bf16_f32 v34, v28, v29
	v_cvt_pk_bf16_f32 v35, v30, v31
	v_cvt_pk_bf16_f32 v36, v24, v25
	v_cvt_pk_bf16_f32 v37, v26, v27
	global_store_dwordx4 v[46:47], v[34:37], off
	s_nop 1
	s_nop 0
	v_mul_f32_e32 v29, v29, v29
	v_mul_f32_e32 v31, v31, v31
	v_mul_f32_e32 v25, v25, v25
	v_fmac_f32_e32 v29, v28, v28
	v_fmac_f32_e32 v31, v30, v30
	v_mul_f32_e32 v27, v27, v27
	v_fmac_f32_e32 v25, v24, v24
	v_add_f32_e32 v24, v29, v31
	v_fmac_f32_e32 v27, v26, v26
	v_add_f32_e32 v24, v24, v25
	v_add_f32_e32 v28, v27, v24
	v_pk_add_f32 v[22:23], v[22:23], v[194:195]
	v_pk_add_f32 v[20:21], v[20:21], v[192:193]
	v_pk_add_f32 v[24:25], v[16:17], v[196:197]
	v_mul_f32_e32 v16, v21, v21
	v_mul_f32_e32 v17, v23, v23
	v_pk_add_f32 v[26:27], v[18:19], v[198:199]
	v_mul_f32_e32 v18, v25, v25
	v_fmac_f32_e32 v16, v20, v20
	v_fmac_f32_e32 v17, v22, v22
	v_mul_f32_e32 v19, v27, v27
	v_fmac_f32_e32 v18, v24, v24
	v_add_f32_e32 v16, v16, v17
	v_add_f32_e32 v16, v16, v18
	v_fmac_f32_e32 v19, v26, v26
	v_add_f32_e32 v16, v19, v16
	v_add_f32_e32 v16, v28, v16
	ds_bpermute_b32 v17, v176, v16
	global_store_dwordx4 v[42:43], v[20:23], off offset:512
	global_store_dwordx4 v[42:43], v[24:27], off offset:528
	v_cvt_pk_bf16_f32 v18, v20, v21
	v_cvt_pk_bf16_f32 v19, v22, v23
	s_waitcnt lgkmcnt(0)
	v_add_f32_e32 v16, v16, v17
	ds_bpermute_b32 v17, v177, v16
	v_cvt_pk_bf16_f32 v20, v24, v25
	v_cvt_pk_bf16_f32 v21, v26, v27
	global_store_dwordx4 v[46:47], v[18:21], off offset:256
	s_and_saveexec_b64 s[50:51], s[6:7]
	s_cbranch_execz .LBB0_1446
	v_lshl_add_u64 v[18:19], v[32:33], 2, s[38:39]
	s_waitcnt lgkmcnt(0)
	v_add_f32_e32 v16, v16, v17
	global_atomic_add_f32 v[18:19], v16, off
.LBB0_1446:
	s_or_b64 exec, exec, s[50:51]
	v_or_b32_e32 v16, 0xb0, v148
	s_waitcnt lgkmcnt(0)
	v_ashrrev_i32_e32 v17, 31, v16
	v_lshlrev_b64 v[26:27], 13, v[16:17]
	v_lshl_add_u64 v[18:19], s[0:1], 0, v[26:27]
	v_lshl_add_u64 v[28:29], v[18:19], 0, v[146:147]
	s_nop 1
	v_lshlrev_b64 v[30:31], 12, v[16:17]
	v_lshl_add_u64 v[26:27], s[10:11], 0, v[26:27]
	v_lshl_add_u64 v[30:31], s[16:17], 0, v[30:31]
	v_lshl_add_u64 v[26:27], v[26:27], 0, v[146:147]
	v_lshl_add_u64 v[30:31], v[144:145], 1, v[30:31]
	s_waitcnt vmcnt(10)
	v_pk_add_f32 v[14:15], v[14:15], v[202:203]
	v_pk_add_f32 v[12:13], v[12:13], v[200:201]
	v_pk_add_f32 v[10:11], v[10:11], v[206:207]
	v_pk_add_f32 v[8:9], v[8:9], v[204:205]
	global_store_dwordx4 v[26:27], v[12:15], off
	global_store_dwordx4 v[26:27], v[8:11], off offset:16
	v_cvt_pk_bf16_f32 v18, v12, v13
	v_cvt_pk_bf16_f32 v19, v14, v15
	v_cvt_pk_bf16_f32 v20, v8, v9
	v_cvt_pk_bf16_f32 v21, v10, v11
	global_store_dwordx4 v[30:31], v[18:21], off
	s_nop 1
	s_nop 0
	v_mul_f32_e32 v13, v13, v13
	v_mul_f32_e32 v15, v15, v15
	v_mul_f32_e32 v9, v9, v9
	v_fmac_f32_e32 v13, v12, v12
	v_fmac_f32_e32 v15, v14, v14
	v_mul_f32_e32 v11, v11, v11
	v_fmac_f32_e32 v9, v8, v8
	v_add_f32_e32 v8, v13, v15
	v_fmac_f32_e32 v11, v10, v10
	v_add_f32_e32 v8, v8, v9
	v_add_f32_e32 v12, v11, v8
	v_pk_add_f32 v[6:7], v[6:7], v[210:211]
	v_pk_add_f32 v[4:5], v[4:5], v[208:209]
	v_pk_add_f32 v[8:9], v[0:1], v[212:213]
	v_mul_f32_e32 v0, v5, v5
	v_mul_f32_e32 v1, v7, v7
	v_pk_add_f32 v[10:11], v[2:3], v[214:215]
	v_mul_f32_e32 v2, v9, v9
	v_fmac_f32_e32 v0, v4, v4
	v_fmac_f32_e32 v1, v6, v6
	v_mul_f32_e32 v3, v11, v11
	v_fmac_f32_e32 v2, v8, v8
	v_add_f32_e32 v0, v0, v1
	v_add_f32_e32 v0, v0, v2
	v_fmac_f32_e32 v3, v10, v10
	v_add_f32_e32 v0, v3, v0
	v_add_f32_e32 v0, v12, v0
	ds_bpermute_b32 v1, v176, v0
	global_store_dwordx4 v[26:27], v[4:7], off offset:512
	global_store_dwordx4 v[26:27], v[8:11], off offset:528
	v_cvt_pk_bf16_f32 v2, v4, v5
	v_cvt_pk_bf16_f32 v3, v6, v7
	s_waitcnt lgkmcnt(0)
	v_add_f32_e32 v0, v0, v1
	ds_bpermute_b32 v1, v177, v0
	v_cvt_pk_bf16_f32 v4, v8, v9
	v_cvt_pk_bf16_f32 v5, v10, v11
	global_store_dwordx4 v[30:31], v[2:5], off offset:256
	s_and_saveexec_b64 s[50:51], s[6:7]
	s_cbranch_execz .LBB0_1448
	v_lshl_add_u64 v[2:3], v[16:17], 2, s[38:39]
	s_waitcnt lgkmcnt(0)
	v_add_f32_e32 v0, v0, v1
	global_atomic_add_f32 v[2:3], v0, off

.LBB0_1602:
	v_lshl_or_b32 v146, s44, 8, v149
	v_lshl_or_b32 v144, s46, 8, v150
	v_ashrrev_i32_e32 v147, 31, v146
	v_lshlrev_b64 v[162:163], 13, v[146:147]
	v_ashrrev_i32_e32 v145, 31, v144
	v_lshl_add_u64 v[154:155], s[0:1], 0, v[162:163]
	v_lshlrev_b64 v[144:145], 2, v[144:145]
	v_lshl_add_u64 v[164:165], v[154:155], 0, v[144:145]
	s_mov_b32 s98, 0x20000
	s_mov_b32 s99, 0
	s_mov_b32 s100, 0xa0000
	s_mov_b32 s101, 0
	global_load_dwordx4 v[184:187], v[164:165], off
	global_load_dwordx4 v[188:191], v[164:165], off offset:16
	global_load_dwordx4 v[192:195], v[164:165], off offset:512
	global_load_dwordx4 v[196:199], v[164:165], off offset:528
	v_lshl_add_u64 v[216:217], v[164:165], 0, s[98:99]
	global_load_dwordx4 v[200:203], v[216:217], off
	global_load_dwordx4 v[204:207], v[216:217], off offset:16
	global_load_dwordx4 v[208:211], v[216:217], off offset:512
	global_load_dwordx4 v[212:215], v[216:217], off offset:528
	s_nop 1
	v_lshl_add_u64 v[162:163], s[8:9], 0, v[162:163]
	v_lshl_add_u64 v[162:163], v[162:163], 0, v[144:145]
	s_waitcnt vmcnt(3)
	v_pk_add_f32 v[126:127], v[126:127], v[186:187]
	v_pk_add_f32 v[124:125], v[124:125], v[184:185]
	v_pk_add_f32 v[122:123], v[122:123], v[190:191]
	v_pk_add_f32 v[120:121], v[120:121], v[188:189]
	global_store_dwordx4 v[162:163], v[124:127], off
	global_store_dwordx4 v[162:163], v[120:123], off offset:16
	s_nop 1
	v_mul_f32_e32 v125, v125, v125
	v_mul_f32_e32 v127, v127, v127
	v_mul_f32_e32 v121, v121, v121
	v_fmac_f32_e32 v125, v124, v124
	v_fmac_f32_e32 v127, v126, v126
	v_mul_f32_e32 v123, v123, v123
	v_fmac_f32_e32 v121, v120, v120
	v_add_f32_e32 v120, v125, v127
	v_fmac_f32_e32 v123, v122, v122
	v_add_f32_e32 v120, v120, v121
	v_add_f32_e32 v124, v123, v120
	v_pk_add_f32 v[118:119], v[118:119], v[194:195]
	v_pk_add_f32 v[116:117], v[116:117], v[192:193]
	v_pk_add_f32 v[120:121], v[112:113], v[196:197]
	v_mul_f32_e32 v112, v117, v117
	v_mul_f32_e32 v113, v119, v119
	v_pk_add_f32 v[122:123], v[114:115], v[198:199]
	v_lshl_add_u64 v[216:217], v[216:217], 0, s[98:99]
	global_load_dwordx4 v[184:187], v[216:217], off
	global_load_dwordx4 v[188:191], v[216:217], off offset:16
	global_load_dwordx4 v[192:195], v[216:217], off offset:512
	global_load_dwordx4 v[196:199], v[216:217], off offset:528
	v_mul_f32_e32 v114, v121, v121
	v_fmac_f32_e32 v112, v116, v116
	v_fmac_f32_e32 v113, v118, v118
	v_mul_f32_e32 v115, v123, v123
	v_fmac_f32_e32 v114, v120, v120
	v_add_f32_e32 v112, v112, v113
	v_add_f32_e32 v112, v112, v114
	v_fmac_f32_e32 v115, v122, v122
	v_add_f32_e32 v112, v115, v112
	v_add_f32_e32 v112, v124, v112
	ds_bpermute_b32 v113, v176, v112
	global_store_dwordx4 v[162:163], v[116:119], off offset:512
	global_store_dwordx4 v[162:163], v[120:123], off offset:528
	s_waitcnt lgkmcnt(0)
	v_add_f32_e32 v112, v112, v113
	ds_bpermute_b32 v113, v177, v112
	s_and_saveexec_b64 s[44:45], s[4:5]
	s_cbranch_execz .LBB0_1604
	v_lshl_add_u64 v[114:115], v[146:147], 2, s[14:15]
	s_waitcnt lgkmcnt(0)
	v_add_f32_e32 v112, v112, v113
	global_atomic_add_f32 v[114:115], v112, off
.LBB0_1604:
	s_or_b64 exec, exec, s[44:45]
	v_or_b32_e32 v112, 16, v146
	s_waitcnt lgkmcnt(0)
	v_ashrrev_i32_e32 v113, 31, v112
	v_lshlrev_b64 v[122:123], 13, v[112:113]
	v_lshl_add_u64 v[114:115], s[0:1], 0, v[122:123]
	v_lshl_add_u64 v[124:125], v[114:115], 0, v[144:145]
	s_nop 1
	v_lshl_add_u64 v[122:123], s[8:9], 0, v[122:123]
	v_lshl_add_u64 v[122:123], v[122:123], 0, v[144:145]
	s_waitcnt vmcnt(8)
	v_pk_add_f32 v[110:111], v[110:111], v[202:203]
	v_pk_add_f32 v[108:109], v[108:109], v[200:201]
	v_pk_add_f32 v[106:107], v[106:107], v[206:207]
	v_pk_add_f32 v[104:105], v[104:105], v[204:205]
	global_store_dwordx4 v[122:123], v[108:111], off
	global_store_dwordx4 v[122:123], v[104:107], off offset:16
	s_nop 1
	v_mul_f32_e32 v109, v109, v109
	v_mul_f32_e32 v111, v111, v111
	v_mul_f32_e32 v105, v105, v105
	v_fmac_f32_e32 v109, v108, v108
	v_fmac_f32_e32 v111, v110, v110
	v_mul_f32_e32 v107, v107, v107
	v_fmac_f32_e32 v105, v104, v104
	v_add_f32_e32 v104, v109, v111
	v_fmac_f32_e32 v107, v106, v106
	v_add_f32_e32 v104, v104, v105
	v_add_f32_e32 v108, v107, v104
	v_pk_add_f32 v[102:103], v[102:103], v[210:211]
	v_pk_add_f32 v[100:101], v[100:101], v[208:209]
	v_pk_add_f32 v[104:105], v[96:97], v[212:213]
	v_mul_f32_e32 v96, v101, v101
	v_mul_f32_e32 v97, v103, v103
	v_pk_add_f32 v[106:107], v[98:99], v[214:215]
	v_lshl_add_u64 v[216:217], v[216:217], 0, s[98:99]
	global_load_dwordx4 v[200:203], v[216:217], off
	global_load_dwordx4 v[204:207], v[216:217], off offset:16
	global_load_dwordx4 v[208:211], v[216:217], off offset:512
	global_load_dwordx4 v[212:215], v[216:217], off offset:528
	v_mul_f32_e32 v98, v105, v105
	v_fmac_f32_e32 v96, v100, v100
	v_fmac_f32_e32 v97, v102, v102
	v_mul_f32_e32 v99, v107, v107
	v_fmac_f32_e32 v98, v104, v104
	v_add_f32_e32 v96, v96, v97
	v_add_f32_e32 v96, v96, v98
	v_fmac_f32_e32 v99, v106, v106
	v_add_f32_e32 v96, v99, v96
	v_add_f32_e32 v96, v108, v96
	ds_bpermute_b32 v97, v176, v96
	global_store_dwordx4 v[122:123], v[100:103], off offset:512
	global_store_dwordx4 v[122:123], v[104:107], off offset:528
	s_waitcnt lgkmcnt(0)
	v_add_f32_e32 v96, v96, v97
	ds_bpermute_b32 v97, v177, v96
	s_and_saveexec_b64 s[44:45], s[4:5]
	s_cbranch_execz .LBB0_1606
	v_lshl_add_u64 v[98:99], v[112:113], 2, s[14:15]
	s_waitcnt lgkmcnt(0)
	v_add_f32_e32 v96, v96, v97
	global_atomic_add_f32 v[98:99], v96, off
.LBB0_1606:
	s_or_b64 exec, exec, s[44:45]
	v_or_b32_e32 v96, 32, v146
	s_waitcnt lgkmcnt(0)
	v_ashrrev_i32_e32 v97, 31, v96
	v_lshlrev_b64 v[106:107], 13, v[96:97]
	v_lshl_add_u64 v[98:99], s[0:1], 0, v[106:107]
	v_lshl_add_u64 v[108:109], v[98:99], 0, v[144:145]
	s_nop 1
	v_lshl_add_u64 v[106:107], s[8:9], 0, v[106:107]
	v_lshl_add_u64 v[106:107], v[106:107], 0, v[144:145]
	s_waitcnt vmcnt(11)
	v_pk_add_f32 v[94:95], v[94:95], v[186:187]
	v_pk_add_f32 v[92:93], v[92:93], v[184:185]
	v_pk_add_f32 v[90:91], v[90:91], v[190:191]
	v_pk_add_f32 v[88:89], v[88:89], v[188:189]
	global_store_dwordx4 v[106:107], v[92:95], off
	global_store_dwordx4 v[106:107], v[88:91], off offset:16
	s_nop 1
	v_mul_f32_e32 v93, v93, v93
	v_mul_f32_e32 v95, v95, v95
	v_mul_f32_e32 v89, v89, v89
	v_fmac_f32_e32 v93, v92, v92
	v_fmac_f32_e32 v95, v94, v94
	v_mul_f32_e32 v91, v91, v91
	v_fmac_f32_e32 v89, v88, v88
	v_add_f32_e32 v88, v93, v95
	v_fmac_f32_e32 v91, v90, v90
	v_add_f32_e32 v88, v88, v89
	v_add_f32_e32 v92, v91, v88
	v_pk_add_f32 v[86:87], v[86:87], v[194:195]
	v_pk_add_f32 v[84:85], v[84:85], v[192:193]
	v_pk_add_f32 v[88:89], v[80:81], v[196:197]
	v_mul_f32_e32 v80, v85, v85
	v_mul_f32_e32 v81, v87, v87
	v_pk_add_f32 v[90:91], v[82:83], v[198:199]
	v_lshl_add_u64 v[216:217], v[216:217], 0, s[100:101]
	global_load_dwordx4 v[184:187], v[216:217], off
	global_load_dwordx4 v[188:191], v[216:217], off offset:16
	global_load_dwordx4 v[192:195], v[216:217], off offset:512
	global_load_dwordx4 v[196:199], v[216:217], off offset:528
	v_mul_f32_e32 v82, v89, v89
	v_fmac_f32_e32 v80, v84, v84
	v_fmac_f32_e32 v81, v86, v86
	v_mul_f32_e32 v83, v91, v91
	v_fmac_f32_e32 v82, v88, v88
	v_add_f32_e32 v80, v80, v81
	v_add_f32_e32 v80, v80, v82
	v_fmac_f32_e32 v83, v90, v90
	v_add_f32_e32 v80, v83, v80
	v_add_f32_e32 v80, v92, v80
	ds_bpermute_b32 v81, v176, v80
	global_store_dwordx4 v[106:107], v[84:87], off offset:512
	global_store_dwordx4 v[106:107], v[88:91], off offset:528
	s_waitcnt lgkmcnt(0)
	v_add_f32_e32 v80, v80, v81
	ds_bpermute_b32 v81, v177, v80
	s_and_saveexec_b64 s[44:45], s[4:5]
	s_cbranch_execz .LBB0_1608
	v_lshl_add_u64 v[82:83], v[96:97], 2, s[14:15]
	s_waitcnt lgkmcnt(0)
	v_add_f32_e32 v80, v80, v81
	global_atomic_add_f32 v[82:83], v80, off
.LBB0_1608:
	s_or_b64 exec, exec, s[44:45]
	v_or_b32_e32 v80, 48, v146
	s_waitcnt lgkmcnt(0)
	v_ashrrev_i32_e32 v81, 31, v80
	v_lshlrev_b64 v[90:91], 13, v[80:81]
	v_lshl_add_u64 v[82:83], s[0:1], 0, v[90:91]
	v_lshl_add_u64 v[92:93], v[82:83], 0, v[144:145]
	s_nop 1
	v_lshl_add_u64 v[90:91], s[8:9], 0, v[90:91]
	v_lshl_add_u64 v[90:91], v[90:91], 0, v[144:145]
	s_waitcnt vmcnt(11)
	v_pk_add_f32 v[78:79], v[78:79], v[202:203]
	v_pk_add_f32 v[76:77], v[76:77], v[200:201]
	v_pk_add_f32 v[74:75], v[74:75], v[206:207]
	v_pk_add_f32 v[72:73], v[72:73], v[204:205]
	global_store_dwordx4 v[90:91], v[76:79], off
	global_store_dwordx4 v[90:91], v[72:75], off offset:16
	s_nop 1
	v_mul_f32_e32 v77, v77, v77
	v_mul_f32_e32 v79, v79, v79
	v_mul_f32_e32 v73, v73, v73
	v_fmac_f32_e32 v77, v76, v76
	v_fmac_f32_e32 v79, v78, v78
	v_mul_f32_e32 v75, v75, v75
	v_fmac_f32_e32 v73, v72, v72
	v_add_f32_e32 v72, v77, v79
	v_fmac_f32_e32 v75, v74, v74
	v_add_f32_e32 v72, v72, v73
	v_add_f32_e32 v76, v75, v72
	v_pk_add_f32 v[70:71], v[70:71], v[210:211]
	v_pk_add_f32 v[68:69], v[68:69], v[208:209]
	v_pk_add_f32 v[72:73], v[64:65], v[212:213]
	v_mul_f32_e32 v64, v69, v69
	v_mul_f32_e32 v65, v71, v71
	v_pk_add_f32 v[74:75], v[66:67], v[214:215]
	v_lshl_add_u64 v[216:217], v[216:217], 0, s[98:99]
	global_load_dwordx4 v[200:203], v[216:217], off
	global_load_dwordx4 v[204:207], v[216:217], off offset:16
	global_load_dwordx4 v[208:211], v[216:217], off offset:512
	global_load_dwordx4 v[212:215], v[216:217], off offset:528
	v_mul_f32_e32 v66, v73, v73
	v_fmac_f32_e32 v64, v68, v68
	v_fmac_f32_e32 v65, v70, v70
	v_mul_f32_e32 v67, v75, v75
	v_fmac_f32_e32 v66, v72, v72
	v_add_f32_e32 v64, v64, v65
	v_add_f32_e32 v64, v64, v66
	v_fmac_f32_e32 v67, v74, v74
	v_add_f32_e32 v64, v67, v64
	v_add_f32_e32 v64, v76, v64
	ds_bpermute_b32 v65, v176, v64
	global_store_dwordx4 v[90:91], v[68:71], off offset:512
	global_store_dwordx4 v[90:91], v[72:75], off offset:528
	s_waitcnt lgkmcnt(0)
	v_add_f32_e32 v64, v64, v65
	ds_bpermute_b32 v65, v177, v64
	s_and_saveexec_b64 s[44:45], s[4:5]
	s_cbranch_execz .LBB0_1610
	v_lshl_add_u64 v[66:67], v[80:81], 2, s[14:15]
	s_waitcnt lgkmcnt(0)
	v_add_f32_e32 v64, v64, v65
	global_atomic_add_f32 v[66:67], v64, off
.LBB0_1610:
	s_or_b64 exec, exec, s[44:45]
	v_or_b32_e32 v64, 0x80, v146
	s_waitcnt lgkmcnt(0)
	v_ashrrev_i32_e32 v65, 31, v64
	v_lshlrev_b64 v[74:75], 13, v[64:65]
	v_lshl_add_u64 v[66:67], s[0:1], 0, v[74:75]
	v_lshl_add_u64 v[76:77], v[66:67], 0, v[144:145]
	s_nop 1
	v_lshl_add_u64 v[74:75], s[8:9], 0, v[74:75]
	v_lshl_add_u64 v[74:75], v[74:75], 0, v[144:145]
	s_waitcnt vmcnt(11)
	v_pk_add_f32 v[62:63], v[62:63], v[186:187]
	v_pk_add_f32 v[60:61], v[60:61], v[184:185]
	v_pk_add_f32 v[58:59], v[58:59], v[190:191]
	v_pk_add_f32 v[56:57], v[56:57], v[188:189]
	global_store_dwordx4 v[74:75], v[60:63], off
	global_store_dwordx4 v[74:75], v[56:59], off offset:16
	s_nop 1
	v_mul_f32_e32 v61, v61, v61
	v_mul_f32_e32 v63, v63, v63
	v_mul_f32_e32 v57, v57, v57
	v_fmac_f32_e32 v61, v60, v60
	v_fmac_f32_e32 v63, v62, v62
	v_mul_f32_e32 v59, v59, v59
	v_fmac_f32_e32 v57, v56, v56
	v_add_f32_e32 v56, v61, v63
	v_fmac_f32_e32 v59, v58, v58
	v_add_f32_e32 v56, v56, v57
	v_add_f32_e32 v60, v59, v56
	v_pk_add_f32 v[54:55], v[54:55], v[194:195]
	v_pk_add_f32 v[52:53], v[52:53], v[192:193]
	v_pk_add_f32 v[56:57], v[48:49], v[196:197]
	v_mul_f32_e32 v48, v53, v53
	v_mul_f32_e32 v49, v55, v55
	v_pk_add_f32 v[58:59], v[50:51], v[198:199]
	v_lshl_add_u64 v[216:217], v[216:217], 0, s[98:99]
	global_load_dwordx4 v[184:187], v[216:217], off
	global_load_dwordx4 v[188:191], v[216:217], off offset:16
	global_load_dwordx4 v[192:195], v[216:217], off offset:512
	global_load_dwordx4 v[196:199], v[216:217], off offset:528
	v_mul_f32_e32 v50, v57, v57
	v_fmac_f32_e32 v48, v52, v52
	v_fmac_f32_e32 v49, v54, v54
	v_mul_f32_e32 v51, v59, v59
	v_fmac_f32_e32 v50, v56, v56
	v_add_f32_e32 v48, v48, v49
	v_add_f32_e32 v48, v48, v50
	v_fmac_f32_e32 v51, v58, v58
	v_add_f32_e32 v48, v51, v48
	v_add_f32_e32 v48, v60, v48
	ds_bpermute_b32 v49, v176, v48
	global_store_dwordx4 v[74:75], v[52:55], off offset:512
	global_store_dwordx4 v[74:75], v[56:59], off offset:528
	s_waitcnt lgkmcnt(0)
	v_add_f32_e32 v48, v48, v49
	ds_bpermute_b32 v49, v177, v48
	s_and_saveexec_b64 s[44:45], s[4:5]
	s_cbranch_execz .LBB0_1612
	v_lshl_add_u64 v[50:51], v[64:65], 2, s[14:15]
	s_waitcnt lgkmcnt(0)
	v_add_f32_e32 v48, v48, v49
	global_atomic_add_f32 v[50:51], v48, off
.LBB0_1612:
	s_or_b64 exec, exec, s[44:45]
	v_or_b32_e32 v48, 0x90, v146
	s_waitcnt lgkmcnt(0)
	v_ashrrev_i32_e32 v49, 31, v48
	v_lshlrev_b64 v[58:59], 13, v[48:49]
	v_lshl_add_u64 v[50:51], s[0:1], 0, v[58:59]
	v_lshl_add_u64 v[60:61], v[50:51], 0, v[144:145]
	s_nop 1
	v_lshl_add_u64 v[58:59], s[8:9], 0, v[58:59]
	v_lshl_add_u64 v[58:59], v[58:59], 0, v[144:145]
	s_waitcnt vmcnt(11)
	v_pk_add_f32 v[46:47], v[46:47], v[202:203]
	v_pk_add_f32 v[44:45], v[44:45], v[200:201]
	v_pk_add_f32 v[42:43], v[42:43], v[206:207]
	v_pk_add_f32 v[40:41], v[40:41], v[204:205]
	global_store_dwordx4 v[58:59], v[44:47], off
	global_store_dwordx4 v[58:59], v[40:43], off offset:16
	s_nop 1
	v_mul_f32_e32 v45, v45, v45
	v_mul_f32_e32 v47, v47, v47
	v_mul_f32_e32 v41, v41, v41
	v_fmac_f32_e32 v45, v44, v44
	v_fmac_f32_e32 v47, v46, v46
	v_mul_f32_e32 v43, v43, v43
	v_fmac_f32_e32 v41, v40, v40
	v_add_f32_e32 v40, v45, v47
	v_fmac_f32_e32 v43, v42, v42
	v_add_f32_e32 v40, v40, v41
	v_add_f32_e32 v44, v43, v40
	v_pk_add_f32 v[38:39], v[38:39], v[210:211]
	v_pk_add_f32 v[36:37], v[36:37], v[208:209]
	v_pk_add_f32 v[40:41], v[32:33], v[212:213]
	v_mul_f32_e32 v32, v37, v37
	v_mul_f32_e32 v33, v39, v39
	v_pk_add_f32 v[42:43], v[34:35], v[214:215]
	v_lshl_add_u64 v[216:217], v[216:217], 0, s[98:99]
	global_load_dwordx4 v[200:203], v[216:217], off
	global_load_dwordx4 v[204:207], v[216:217], off offset:16
	global_load_dwordx4 v[208:211], v[216:217], off offset:512
	global_load_dwordx4 v[212:215], v[216:217], off offset:528
	v_mul_f32_e32 v34, v41, v41
	v_fmac_f32_e32 v32, v36, v36
	v_fmac_f32_e32 v33, v38, v38
	v_mul_f32_e32 v35, v43, v43
	v_fmac_f32_e32 v34, v40, v40
	v_add_f32_e32 v32, v32, v33
	v_add_f32_e32 v32, v32, v34
	v_fmac_f32_e32 v35, v42, v42
	v_add_f32_e32 v32, v35, v32
	v_add_f32_e32 v32, v44, v32
	ds_bpermute_b32 v33, v176, v32
	global_store_dwordx4 v[58:59], v[36:39], off offset:512
	global_store_dwordx4 v[58:59], v[40:43], off offset:528
	s_waitcnt lgkmcnt(0)
	v_add_f32_e32 v32, v32, v33
	ds_bpermute_b32 v33, v177, v32
	s_and_saveexec_b64 s[44:45], s[4:5]
	s_cbranch_execz .LBB0_1614
	v_lshl_add_u64 v[34:35], v[48:49], 2, s[14:15]
	s_waitcnt lgkmcnt(0)
	v_add_f32_e32 v32, v32, v33
	global_atomic_add_f32 v[34:35], v32, off
.LBB0_1614:
	s_or_b64 exec, exec, s[44:45]
	v_or_b32_e32 v32, 0xa0, v146
	s_waitcnt lgkmcnt(0)
	v_ashrrev_i32_e32 v33, 31, v32
	v_lshlrev_b64 v[42:43], 13, v[32:33]
	v_lshl_add_u64 v[34:35], s[0:1], 0, v[42:43]
	v_lshl_add_u64 v[44:45], v[34:35], 0, v[144:145]
	s_nop 1
	v_lshl_add_u64 v[42:43], s[8:9], 0, v[42:43]
	v_lshl_add_u64 v[42:43], v[42:43], 0, v[144:145]
	s_waitcnt vmcnt(11)
	v_pk_add_f32 v[30:31], v[30:31], v[186:187]
	v_pk_add_f32 v[28:29], v[28:29], v[184:185]
	v_pk_add_f32 v[26:27], v[26:27], v[190:191]
	v_pk_add_f32 v[24:25], v[24:25], v[188:189]
	global_store_dwordx4 v[42:43], v[28:31], off
	global_store_dwordx4 v[42:43], v[24:27], off offset:16
	s_nop 1
	v_mul_f32_e32 v29, v29, v29
	v_mul_f32_e32 v31, v31, v31
	v_mul_f32_e32 v25, v25, v25
	v_fmac_f32_e32 v29, v28, v28
	v_fmac_f32_e32 v31, v30, v30
	v_mul_f32_e32 v27, v27, v27
	v_fmac_f32_e32 v25, v24, v24
	v_add_f32_e32 v24, v29, v31
	v_fmac_f32_e32 v27, v26, v26
	v_add_f32_e32 v24, v24, v25
	v_add_f32_e32 v28, v27, v24
	v_pk_add_f32 v[22:23], v[22:23], v[194:195]
	v_pk_add_f32 v[20:21], v[20:21], v[192:193]
	v_pk_add_f32 v[24:25], v[16:17], v[196:197]
	v_mul_f32_e32 v16, v21, v21
	v_mul_f32_e32 v17, v23, v23
	v_pk_add_f32 v[26:27], v[18:19], v[198:199]
	v_mul_f32_e32 v18, v25, v25
	v_fmac_f32_e32 v16, v20, v20
	v_fmac_f32_e32 v17, v22, v22
	v_mul_f32_e32 v19, v27, v27
	v_fmac_f32_e32 v18, v24, v24
	v_add_f32_e32 v16, v16, v17
	v_add_f32_e32 v16, v16, v18
	v_fmac_f32_e32 v19, v26, v26
	v_add_f32_e32 v16, v19, v16
	v_add_f32_e32 v16, v28, v16
	ds_bpermute_b32 v17, v176, v16
	global_store_dwordx4 v[42:43], v[20:23], off offset:512
	global_store_dwordx4 v[42:43], v[24:27], off offset:528
	s_waitcnt lgkmcnt(0)
	v_add_f32_e32 v16, v16, v17
	ds_bpermute_b32 v17, v177, v16
	s_and_saveexec_b64 s[44:45], s[4:5]
	s_cbranch_execz .LBB0_1616
	v_lshl_add_u64 v[18:19], v[32:33], 2, s[14:15]
	s_waitcnt lgkmcnt(0)
	v_add_f32_e32 v16, v16, v17
	global_atomic_add_f32 v[18:19], v16, off
.LBB0_1616:
	s_or_b64 exec, exec, s[44:45]
	v_or_b32_e32 v16, 0xb0, v146
	s_waitcnt lgkmcnt(0)
	v_ashrrev_i32_e32 v17, 31, v16
	v_lshlrev_b64 v[26:27], 13, v[16:17]
	v_lshl_add_u64 v[18:19], s[0:1], 0, v[26:27]
	v_lshl_add_u64 v[28:29], v[18:19], 0, v[144:145]
	s_nop 1
	v_lshl_add_u64 v[26:27], s[8:9], 0, v[26:27]
	v_lshl_add_u64 v[26:27], v[26:27], 0, v[144:145]
	s_waitcnt vmcnt(7)
	v_pk_add_f32 v[14:15], v[14:15], v[202:203]
	v_pk_add_f32 v[12:13], v[12:13], v[200:201]
	v_pk_add_f32 v[10:11], v[10:11], v[206:207]
	v_pk_add_f32 v[8:9], v[8:9], v[204:205]
	global_store_dwordx4 v[26:27], v[12:15], off
	global_store_dwordx4 v[26:27], v[8:11], off offset:16
	s_nop 1
	v_mul_f32_e32 v13, v13, v13
	v_mul_f32_e32 v15, v15, v15
	v_mul_f32_e32 v9, v9, v9
	v_fmac_f32_e32 v13, v12, v12
	v_fmac_f32_e32 v15, v14, v14
	v_mul_f32_e32 v11, v11, v11
	v_fmac_f32_e32 v9, v8, v8
	v_add_f32_e32 v8, v13, v15
	v_fmac_f32_e32 v11, v10, v10
	v_add_f32_e32 v8, v8, v9
	v_add_f32_e32 v12, v11, v8
	v_pk_add_f32 v[6:7], v[6:7], v[210:211]
	v_pk_add_f32 v[4:5], v[4:5], v[208:209]
	v_pk_add_f32 v[8:9], v[0:1], v[212:213]
	v_mul_f32_e32 v0, v5, v5
	v_mul_f32_e32 v1, v7, v7
	v_pk_add_f32 v[10:11], v[2:3], v[214:215]
	v_mul_f32_e32 v2, v9, v9
	v_fmac_f32_e32 v0, v4, v4
	v_fmac_f32_e32 v1, v6, v6
	v_mul_f32_e32 v3, v11, v11
	v_fmac_f32_e32 v2, v8, v8
	v_add_f32_e32 v0, v0, v1
	v_add_f32_e32 v0, v0, v2
	v_fmac_f32_e32 v3, v10, v10
	v_add_f32_e32 v0, v3, v0
	v_add_f32_e32 v0, v12, v0
	ds_bpermute_b32 v1, v176, v0
	global_store_dwordx4 v[26:27], v[4:7], off offset:512
	global_store_dwordx4 v[26:27], v[8:11], off offset:528
	s_waitcnt lgkmcnt(0)
	v_add_f32_e32 v0, v0, v1
	ds_bpermute_b32 v1, v177, v0
	s_and_saveexec_b64 s[44:45], s[4:5]
	s_cbranch_execz .LBB0_1618
	v_lshl_add_u64 v[2:3], v[16:17], 2, s[14:15]
	s_waitcnt lgkmcnt(0)
	v_add_f32_e32 v0, v0, v1
	global_atomic_add_f32 v[2:3], v0, off
